# P4 epilogue: 6 (ya,sz) load pairs in flight, sigmoid per step, packed f32 math (v_pk_fma/mul/add), scalar row bases
# speedup vs baseline: 1.0123x; 1.0022x over previous
; __device__ __forceinline__ unsigned cvt_pk_bf16(float lo, float hi) { unsigned r; asm volatile("v_cvt_pk_bf16_f32 %0, %1, %2" : "=v"(r) : "v"(lo), "v"(hi)); return r; }
;     __device__ __forceinline__ void operator()(const f32x4 (&acc)[2][2][4][2], const Unit& u, int wr, int wc, int fr, int fq) const {
;         const int row0 = u.pm * BM + wr * 64 + fr, col0 = u.pn * BM + wc * 32 + 8 * fq;
;         const float GATE_DEQ = YA8_R * qr[1] * (1.0f / (::Q8 * ::Q8));
;         f32x4 bv[2][2];
; #pragma unroll
;         for (int bj = 0; bj < 2; ++bj)
; #pragma unroll
;             for (int n = 0; n < 2; ++n) bv[bj][n] = *(const f32x4*)(bias + col0 + bj * HALF + 4 * n);
; #pragma unroll
;         for (int ai = 0; ai < 2; ++ai)
; #pragma unroll
;             for (int m = 0; m < 4; ++m) { const int row = row0 + ai * HALF + m * 16; const size_t off = (size_t)row * EI + col0;
;                 const size_t offy = ((size_t)((row >> 13) * NG + (col0 >> 4)) * SEQ + (row & (SEQ - 1))) * 16 + (col0 & 15);
; #pragma unroll
;                 for (int bj = 0; bj < 2; ++bj) { const u32x4 yv = *(const u32x4*)(YA + offy + (size_t)bj * 8 * SEQ * 16), zv = *(const u32x4*)(SZ + off + bj * HALF);
;                     const i32x4 q0 = __builtin_bit_cast(i32x4, acc[ai][bj][m][0]), q1 = __builtin_bit_cast(i32x4, acc[ai][bj][m][1]);
;                     const f32x4 g0 = (f32x4){(float)q0[0], (float)q0[1], (float)q0[2], (float)q0[3]} * GATE_DEQ + bv[bj][0], g1 = (f32x4){(float)q1[0], (float)q1[1], (float)q1[2], (float)q1[3]} * GATE_DEQ + bv[bj][1];
;                     float o[8];
;                     o[0] = bf_lo(yv.x) * bf_lo(zv.x) * fast_sigmoid(g0[0]); o[1] = bf_hi(yv.x) * bf_hi(zv.x) * fast_sigmoid(g0[1]);
;                     o[2] = bf_lo(yv.y) * bf_lo(zv.y) * fast_sigmoid(g0[2]); o[3] = bf_hi(yv.y) * bf_hi(zv.y) * fast_sigmoid(g0[3]);
;                     o[4] = bf_lo(yv.z) * bf_lo(zv.z) * fast_sigmoid(g1[0]); o[5] = bf_hi(yv.z) * bf_hi(zv.z) * fast_sigmoid(g1[1]);
;                     o[6] = bf_lo(yv.w) * bf_lo(zv.w) * fast_sigmoid(g1[2]); o[7] = bf_hi(yv.w) * bf_hi(zv.w) * fast_sigmoid(g1[3]);
;                     u32x4 w; w.x = cvt_pk_bf16(o[0], o[1]); w.y = cvt_pk_bf16(o[2], o[3]); w.z = cvt_pk_bf16(o[4], o[5]); w.w = cvt_pk_bf16(o[6], o[7]);
;                     *(u32x4*)(V + off + bj * HALF) = w; } }
;     }
.LBB0_502:
	v_lshl_add_u32 v187, s52, 8, v225
	global_load_dword v186, v201, s[22:23]
	v_lshlrev_b32_e32 v188, 2, v187
	s_lshl_b32 s41, s86, 8
	global_load_dwordx4 v[68:71], v188, s[20:21]
	global_load_dwordx4 v[64:67], v188, s[20:21] offset:16
	global_load_dwordx4 v[136:139], v188, s[20:21] offset:512
	global_load_dwordx4 v[140:143], v188, s[20:21] offset:528
	s_add_i32 s41, s41, s75
	v_or_b32_e32 v189, s41, v220
	s_ashr_i32 s41, s41, 4
	v_ashrrev_i32_e32 v190, 4, v187
	s_and_b32 s41, s41, 0xfffffe00
	v_lshlrev_b32_e32 v191, 5, v189
	v_add_u32_e32 v190, s41, v190
	v_and_b32_e32 v191, 0x3f9e0, v191
	v_lshlrev_b32_e32 v190, 18, v190
	v_add3_u32 v184, v190, v191, v206
	v_lshlrev_b32_e32 v191, 1, v187
	v_lshl_add_u32 v239, v189, 14, v191
	v_add_u32_e32 v184, 0x800, v184
	v_mov_b32_e32 v207, v201
	v_add_u32_e32 v185, 0x200000, v184
	s_mov_b64 s[98:99], s[12:13]
	global_load_dwordx4 v[148:151], v239, s[98:99]
	global_load_dwordx4 v[144:147], v184, s[10:11] offset:-2048
	global_load_dwordx4 v[156:159], v239, s[98:99] offset:256
	global_load_dwordx4 v[152:155], v185, s[10:11] offset:-2048
	s_add_u32 s98, s12, 0x40000
	s_addc_u32 s99, s13, 0
	global_load_dwordx4 v[164:167], v239, s[98:99]
	global_load_dwordx4 v[160:163], v184, s[10:11] offset:-1536
	global_load_dwordx4 v[180:183], v239, s[98:99] offset:256
	global_load_dwordx4 v[172:175], v185, s[10:11] offset:-1536
	s_add_u32 s98, s12, 0x80000
	s_addc_u32 s99, s13, 0
	global_load_dwordx4 v[244:247], v239, s[98:99]
	global_load_dwordx4 v[240:243], v184, s[10:11] offset:-1024
	global_load_dwordx4 v[176:179], v239, s[98:99] offset:256
	global_load_dwordx4 v[248:251], v185, s[10:11] offset:-1024
	s_waitcnt vmcnt(12)
	v_mul_f32_e32 v186, 0x41600000, v186
	v_mul_f32_e32 v186, 0x38800200, v186
	s_mov_b32 s32, 0xbfb8aa3b
	v_cvt_f32_i32_e32 v60, v60
	v_cvt_f32_i32_e32 v61, v61
	v_cvt_f32_i32_e32 v62, v62
	v_cvt_f32_i32_e32 v63, v63
	v_cvt_f32_i32_e32 v56, v56
	v_cvt_f32_i32_e32 v57, v57
	v_cvt_f32_i32_e32 v58, v58
	v_cvt_f32_i32_e32 v59, v59
	v_pk_fma_f32 v[60:61], v[186:187], v[60:61], v[68:69] op_sel_hi:[0,1,1]
	v_pk_fma_f32 v[62:63], v[186:187], v[62:63], v[70:71] op_sel_hi:[0,1,1]
	v_pk_fma_f32 v[56:57], v[186:187], v[56:57], v[64:65] op_sel_hi:[0,1,1]
	v_pk_fma_f32 v[58:59], v[186:187], v[58:59], v[66:67] op_sel_hi:[0,1,1]
	v_pk_mul_f32 v[60:61], v[60:61], s[32:33] op_sel_hi:[1,0]
	v_pk_mul_f32 v[62:63], v[62:63], s[32:33] op_sel_hi:[1,0]
	v_pk_mul_f32 v[56:57], v[56:57], s[32:33] op_sel_hi:[1,0]
	v_pk_mul_f32 v[58:59], v[58:59], s[32:33] op_sel_hi:[1,0]
	v_exp_f32_e32 v60, v60
	v_exp_f32_e32 v61, v61
	v_exp_f32_e32 v62, v62
	v_exp_f32_e32 v63, v63
	v_exp_f32_e32 v56, v56
	v_exp_f32_e32 v57, v57
	v_exp_f32_e32 v58, v58
	v_exp_f32_e32 v59, v59
	v_pk_add_f32 v[60:61], v[60:61], 1.0 op_sel_hi:[1,0]
	v_pk_add_f32 v[62:63], v[62:63], 1.0 op_sel_hi:[1,0]
	v_pk_add_f32 v[56:57], v[56:57], 1.0 op_sel_hi:[1,0]
	v_pk_add_f32 v[58:59], v[58:59], 1.0 op_sel_hi:[1,0]
	v_rcp_f32_e32 v60, v60
	v_rcp_f32_e32 v61, v61
	v_rcp_f32_e32 v62, v62
	v_rcp_f32_e32 v63, v63
	v_rcp_f32_e32 v56, v56
	v_rcp_f32_e32 v57, v57
	v_rcp_f32_e32 v58, v58
	v_rcp_f32_e32 v59, v59
	s_waitcnt vmcnt(10)
	v_lshlrev_b32_e32 v168, 16, v144
	v_and_b32_e32 v169, 0xffff0000, v144
	v_lshlrev_b32_e32 v188, 16, v148
	v_and_b32_e32 v189, 0xffff0000, v148
	v_pk_mul_f32 v[168:169], v[168:169], v[188:189]
	v_pk_mul_f32 v[60:61], v[168:169], v[60:61]
	v_lshlrev_b32_e32 v170, 16, v145
	v_and_b32_e32 v171, 0xffff0000, v145
	v_lshlrev_b32_e32 v190, 16, v149
	v_and_b32_e32 v191, 0xffff0000, v149
	v_pk_mul_f32 v[170:171], v[170:171], v[190:191]
	v_pk_mul_f32 v[62:63], v[170:171], v[62:63]
	v_lshlrev_b32_e32 v168, 16, v146
	v_and_b32_e32 v169, 0xffff0000, v146
	v_lshlrev_b32_e32 v188, 16, v150
	v_and_b32_e32 v189, 0xffff0000, v150
	v_pk_mul_f32 v[168:169], v[168:169], v[188:189]
	v_pk_mul_f32 v[56:57], v[168:169], v[56:57]
	v_lshlrev_b32_e32 v170, 16, v147
	v_and_b32_e32 v171, 0xffff0000, v147
	v_lshlrev_b32_e32 v190, 16, v151
	v_and_b32_e32 v191, 0xffff0000, v151
	v_pk_mul_f32 v[170:171], v[170:171], v[190:191]
	v_pk_mul_f32 v[58:59], v[170:171], v[58:59]
	s_add_u32 s98, s12, 0xc0000
	s_addc_u32 s99, s13, 0
	global_load_dwordx4 v[148:151], v239, s[98:99]
	global_load_dwordx4 v[144:147], v184, s[10:11] offset:-512
	v_cvt_pk_bf16_f32 v60, v60, v61
	v_cvt_pk_bf16_f32 v61, v62, v63
	v_cvt_pk_bf16_f32 v62, v56, v57
	v_cvt_pk_bf16_f32 v63, v58, v59
	s_mov_b64 s[100:101], s[16:17]
	global_store_dwordx4 v239, v[60:63], s[100:101]
	v_cvt_f32_i32_e32 v132, v132
	v_cvt_f32_i32_e32 v133, v133
	v_cvt_f32_i32_e32 v134, v134
	v_cvt_f32_i32_e32 v135, v135
	v_cvt_f32_i32_e32 v128, v128
	v_cvt_f32_i32_e32 v129, v129
	v_cvt_f32_i32_e32 v130, v130
	v_cvt_f32_i32_e32 v131, v131
	v_pk_fma_f32 v[132:133], v[186:187], v[132:133], v[136:137] op_sel_hi:[0,1,1]
	v_pk_fma_f32 v[134:135], v[186:187], v[134:135], v[138:139] op_sel_hi:[0,1,1]
	v_pk_fma_f32 v[128:129], v[186:187], v[128:129], v[140:141] op_sel_hi:[0,1,1]
	v_pk_fma_f32 v[130:131], v[186:187], v[130:131], v[142:143] op_sel_hi:[0,1,1]
	v_pk_mul_f32 v[132:133], v[132:133], s[32:33] op_sel_hi:[1,0]
	v_pk_mul_f32 v[134:135], v[134:135], s[32:33] op_sel_hi:[1,0]
	v_pk_mul_f32 v[128:129], v[128:129], s[32:33] op_sel_hi:[1,0]
	v_pk_mul_f32 v[130:131], v[130:131], s[32:33] op_sel_hi:[1,0]
	v_exp_f32_e32 v132, v132
	v_exp_f32_e32 v133, v133
	v_exp_f32_e32 v134, v134
	v_exp_f32_e32 v135, v135
	v_exp_f32_e32 v128, v128
	v_exp_f32_e32 v129, v129
	v_exp_f32_e32 v130, v130
	v_exp_f32_e32 v131, v131
	v_pk_add_f32 v[132:133], v[132:133], 1.0 op_sel_hi:[1,0]
	v_pk_add_f32 v[134:135], v[134:135], 1.0 op_sel_hi:[1,0]
	v_pk_add_f32 v[128:129], v[128:129], 1.0 op_sel_hi:[1,0]
	v_pk_add_f32 v[130:131], v[130:131], 1.0 op_sel_hi:[1,0]
	v_rcp_f32_e32 v132, v132
	v_rcp_f32_e32 v133, v133
	v_rcp_f32_e32 v134, v134
	v_rcp_f32_e32 v135, v135
	v_rcp_f32_e32 v128, v128
	v_rcp_f32_e32 v129, v129
	v_rcp_f32_e32 v130, v130
	v_rcp_f32_e32 v131, v131
	s_waitcnt vmcnt(11)
; __device__ __forceinline__ unsigned cvt_pk_bf16(float lo, float hi) { unsigned r; asm volatile("v_cvt_pk_bf16_f32 %0, %1, %2" : "=v"(r) : "v"(lo), "v"(hi)); return r; }
; __device__ __forceinline__ float bf_lo(unsigned w) { return __uint_as_float(w << 16); }
; __device__ __forceinline__ float bf_hi(unsigned w) { return __uint_as_float(w & 0xffff0000u); }
; __device__ __forceinline__ float fast_sigmoid(float x) { return __builtin_amdgcn_rcpf(1.0f + __builtin_amdgcn_exp2f(-1.4426950408889634f * x)); }
;     __device__ __forceinline__ void operator()(const f32x4 (&acc)[2][2][4][2], const Unit& u, int wr, int wc, int fr, int fq) const {
;     ...
;             for (int m = 0; m < 4; ++m) { const int row = row0 + ai * HALF + m * 16; const size_t off = (size_t)row * EI + col0;
;                 const size_t offy = ((size_t)((row >> 13) * NG + (col0 >> 4)) * SEQ + (row & (SEQ - 1))) * 16 + (col0 & 15);
; #pragma unroll
;                 for (int bj = 0; bj < 2; ++bj) { const u32x4 yv = *(const u32x4*)(YA + offy + (size_t)bj * 8 * SEQ * 16), zv = *(const u32x4*)(SZ + off + bj * HALF);
;                     const i32x4 q0 = __builtin_bit_cast(i32x4, acc[ai][bj][m][0]), q1 = __builtin_bit_cast(i32x4, acc[ai][bj][m][1]);
;                     const f32x4 g0 = (f32x4){(float)q0[0], (float)q0[1], (float)q0[2], (float)q0[3]} * GATE_DEQ + bv[bj][0], g1 = (f32x4){(float)q1[0], (float)q1[1], (float)q1[2], (float)q1[3]} * GATE_DEQ + bv[bj][1];
;                     float o[8];
;                     o[0] = bf_lo(yv.x) * bf_lo(zv.x) * fast_sigmoid(g0[0]); o[1] = bf_hi(yv.x) * bf_hi(zv.x) * fast_sigmoid(g0[1]);
;                     o[2] = bf_lo(yv.y) * bf_lo(zv.y) * fast_sigmoid(g0[2]); o[3] = bf_hi(yv.y) * bf_hi(zv.y) * fast_sigmoid(g0[3]);
;                     o[4] = bf_lo(yv.z) * bf_lo(zv.z) * fast_sigmoid(g1[0]); o[5] = bf_hi(yv.z) * bf_hi(zv.z) * fast_sigmoid(g1[1]);
;                     o[6] = bf_lo(yv.w) * bf_lo(zv.w) * fast_sigmoid(g1[2]); o[7] = bf_hi(yv.w) * bf_hi(zv.w) * fast_sigmoid(g1[3]);
;                     u32x4 w; w.x = cvt_pk_bf16(o[0], o[1]); w.y = cvt_pk_bf16(o[2], o[3]); w.z = cvt_pk_bf16(o[4], o[5]); w.w = cvt_pk_bf16(o[6], o[7]);
;                     *(u32x4*)(V + off + bj * HALF) = w; } }
	v_lshlrev_b32_e32 v168, 16, v152
	v_and_b32_e32 v169, 0xffff0000, v152
	v_lshlrev_b32_e32 v188, 16, v156
	v_and_b32_e32 v189, 0xffff0000, v156
	v_pk_mul_f32 v[168:169], v[168:169], v[188:189]
	v_pk_mul_f32 v[132:133], v[168:169], v[132:133]
	v_lshlrev_b32_e32 v170, 16, v153
	v_and_b32_e32 v171, 0xffff0000, v153
	v_lshlrev_b32_e32 v190, 16, v157
	v_and_b32_e32 v191, 0xffff0000, v157
	v_pk_mul_f32 v[170:171], v[170:171], v[190:191]
	v_pk_mul_f32 v[134:135], v[170:171], v[134:135]
	v_lshlrev_b32_e32 v168, 16, v154
	v_and_b32_e32 v169, 0xffff0000, v154
	v_lshlrev_b32_e32 v188, 16, v158
	v_and_b32_e32 v189, 0xffff0000, v158
	v_pk_mul_f32 v[168:169], v[168:169], v[188:189]
	v_pk_mul_f32 v[128:129], v[168:169], v[128:129]
	v_lshlrev_b32_e32 v170, 16, v155
	v_and_b32_e32 v171, 0xffff0000, v155
	v_lshlrev_b32_e32 v190, 16, v159
	v_and_b32_e32 v191, 0xffff0000, v159
	v_pk_mul_f32 v[170:171], v[170:171], v[190:191]
	v_pk_mul_f32 v[130:131], v[170:171], v[130:131]
	global_load_dwordx4 v[156:159], v239, s[98:99] offset:256
	global_load_dwordx4 v[152:155], v185, s[10:11] offset:-512
	v_cvt_pk_bf16_f32 v132, v132, v133
	v_cvt_pk_bf16_f32 v133, v134, v135
	v_cvt_pk_bf16_f32 v134, v128, v129
	v_cvt_pk_bf16_f32 v135, v130, v131
	global_store_dwordx4 v239, v[132:135], s[100:101] offset:256
	v_cvt_f32_i32_e32 v124, v124
	v_cvt_f32_i32_e32 v125, v125
	v_cvt_f32_i32_e32 v126, v126
	v_cvt_f32_i32_e32 v127, v127
	v_cvt_f32_i32_e32 v120, v120
	v_cvt_f32_i32_e32 v121, v121
	v_cvt_f32_i32_e32 v122, v122
	v_cvt_f32_i32_e32 v123, v123
	v_pk_fma_f32 v[124:125], v[186:187], v[124:125], v[68:69] op_sel_hi:[0,1,1]
	v_pk_fma_f32 v[126:127], v[186:187], v[126:127], v[70:71] op_sel_hi:[0,1,1]
	v_pk_fma_f32 v[120:121], v[186:187], v[120:121], v[64:65] op_sel_hi:[0,1,1]
	v_pk_fma_f32 v[122:123], v[186:187], v[122:123], v[66:67] op_sel_hi:[0,1,1]
	v_pk_mul_f32 v[124:125], v[124:125], s[32:33] op_sel_hi:[1,0]
	v_pk_mul_f32 v[126:127], v[126:127], s[32:33] op_sel_hi:[1,0]
	v_pk_mul_f32 v[120:121], v[120:121], s[32:33] op_sel_hi:[1,0]
	v_pk_mul_f32 v[122:123], v[122:123], s[32:33] op_sel_hi:[1,0]
	v_exp_f32_e32 v124, v124
	v_exp_f32_e32 v125, v125
	v_exp_f32_e32 v126, v126
	v_exp_f32_e32 v127, v127
	v_exp_f32_e32 v120, v120
	v_exp_f32_e32 v121, v121
	v_exp_f32_e32 v122, v122
	v_exp_f32_e32 v123, v123
	v_pk_add_f32 v[124:125], v[124:125], 1.0 op_sel_hi:[1,0]
	v_pk_add_f32 v[126:127], v[126:127], 1.0 op_sel_hi:[1,0]
	v_pk_add_f32 v[120:121], v[120:121], 1.0 op_sel_hi:[1,0]
	v_pk_add_f32 v[122:123], v[122:123], 1.0 op_sel_hi:[1,0]
	v_rcp_f32_e32 v124, v124
	v_rcp_f32_e32 v125, v125
	v_rcp_f32_e32 v126, v126
	v_rcp_f32_e32 v127, v127
	v_rcp_f32_e32 v120, v120
	v_rcp_f32_e32 v121, v121
	v_rcp_f32_e32 v122, v122
	v_rcp_f32_e32 v123, v123
	s_waitcnt vmcnt(12)
	v_lshlrev_b32_e32 v168, 16, v160
	v_and_b32_e32 v169, 0xffff0000, v160
	v_lshlrev_b32_e32 v188, 16, v164
	v_and_b32_e32 v189, 0xffff0000, v164
	v_pk_mul_f32 v[168:169], v[168:169], v[188:189]
	v_pk_mul_f32 v[124:125], v[168:169], v[124:125]
	v_lshlrev_b32_e32 v170, 16, v161
	v_and_b32_e32 v171, 0xffff0000, v161
	v_lshlrev_b32_e32 v190, 16, v165
	v_and_b32_e32 v191, 0xffff0000, v165
	v_pk_mul_f32 v[170:171], v[170:171], v[190:191]
	v_pk_mul_f32 v[126:127], v[170:171], v[126:127]
	v_lshlrev_b32_e32 v168, 16, v162
	v_and_b32_e32 v169, 0xffff0000, v162
	v_lshlrev_b32_e32 v188, 16, v166
	v_and_b32_e32 v189, 0xffff0000, v166
	v_pk_mul_f32 v[168:169], v[168:169], v[188:189]
	v_pk_mul_f32 v[120:121], v[168:169], v[120:121]
	v_lshlrev_b32_e32 v170, 16, v163
	v_and_b32_e32 v171, 0xffff0000, v163
	v_lshlrev_b32_e32 v190, 16, v167
	v_and_b32_e32 v191, 0xffff0000, v167
	v_pk_mul_f32 v[170:171], v[170:171], v[190:191]
	v_pk_mul_f32 v[122:123], v[170:171], v[122:123]
	s_add_u32 s98, s12, 0x200000
	s_addc_u32 s99, s13, 0
	global_load_dwordx4 v[164:167], v239, s[98:99]
	global_load_dwordx4 v[160:163], v184, s[10:11] offset:2048
	v_cvt_pk_bf16_f32 v124, v124, v125
	v_cvt_pk_bf16_f32 v125, v126, v127
	v_cvt_pk_bf16_f32 v126, v120, v121
	v_cvt_pk_bf16_f32 v127, v122, v123
	s_add_u32 s100, s16, 0x40000
	s_addc_u32 s101, s17, 0
	global_store_dwordx4 v239, v[124:127], s[100:101]
	v_cvt_f32_i32_e32 v116, v116
	v_cvt_f32_i32_e32 v117, v117
	v_cvt_f32_i32_e32 v118, v118
	v_cvt_f32_i32_e32 v119, v119
	v_cvt_f32_i32_e32 v112, v112
	v_cvt_f32_i32_e32 v113, v113
	v_cvt_f32_i32_e32 v114, v114
	v_cvt_f32_i32_e32 v115, v115
	v_pk_fma_f32 v[116:117], v[186:187], v[116:117], v[136:137] op_sel_hi:[0,1,1]
	v_pk_fma_f32 v[118:119], v[186:187], v[118:119], v[138:139] op_sel_hi:[0,1,1]
	v_pk_fma_f32 v[112:113], v[186:187], v[112:113], v[140:141] op_sel_hi:[0,1,1]
	v_pk_fma_f32 v[114:115], v[186:187], v[114:115], v[142:143] op_sel_hi:[0,1,1]
	v_pk_mul_f32 v[116:117], v[116:117], s[32:33] op_sel_hi:[1,0]
	v_pk_mul_f32 v[118:119], v[118:119], s[32:33] op_sel_hi:[1,0]
	v_pk_mul_f32 v[112:113], v[112:113], s[32:33] op_sel_hi:[1,0]
	v_pk_mul_f32 v[114:115], v[114:115], s[32:33] op_sel_hi:[1,0]
	v_exp_f32_e32 v116, v116
	v_exp_f32_e32 v117, v117
	v_exp_f32_e32 v118, v118
	v_exp_f32_e32 v119, v119
	v_exp_f32_e32 v112, v112
	v_exp_f32_e32 v113, v113
	v_exp_f32_e32 v114, v114
	v_exp_f32_e32 v115, v115
	v_pk_add_f32 v[116:117], v[116:117], 1.0 op_sel_hi:[1,0]
	v_pk_add_f32 v[118:119], v[118:119], 1.0 op_sel_hi:[1,0]
	v_pk_add_f32 v[112:113], v[112:113], 1.0 op_sel_hi:[1,0]
	v_pk_add_f32 v[114:115], v[114:115], 1.0 op_sel_hi:[1,0]
	v_rcp_f32_e32 v116, v116
	v_rcp_f32_e32 v117, v117
	v_rcp_f32_e32 v118, v118
	v_rcp_f32_e32 v119, v119
	v_rcp_f32_e32 v112, v112
	v_rcp_f32_e32 v113, v113
	v_rcp_f32_e32 v114, v114
	v_rcp_f32_e32 v115, v115
	s_waitcnt vmcnt(13)
; __device__ __forceinline__ unsigned cvt_pk_bf16(float lo, float hi) { unsigned r; asm volatile("v_cvt_pk_bf16_f32 %0, %1, %2" : "=v"(r) : "v"(lo), "v"(hi)); return r; }
; __device__ __forceinline__ float bf_lo(unsigned w) { return __uint_as_float(w << 16); }
; __device__ __forceinline__ float bf_hi(unsigned w) { return __uint_as_float(w & 0xffff0000u); }
; __device__ __forceinline__ float fast_sigmoid(float x) { return __builtin_amdgcn_rcpf(1.0f + __builtin_amdgcn_exp2f(-1.4426950408889634f * x)); }
;     __device__ __forceinline__ void operator()(const f32x4 (&acc)[2][2][4][2], const Unit& u, int wr, int wc, int fr, int fq) const {
;     ...
;             for (int m = 0; m < 4; ++m) { const int row = row0 + ai * HALF + m * 16; const size_t off = (size_t)row * EI + col0;
;                 const size_t offy = ((size_t)((row >> 13) * NG + (col0 >> 4)) * SEQ + (row & (SEQ - 1))) * 16 + (col0 & 15);
; #pragma unroll
;                 for (int bj = 0; bj < 2; ++bj) { const u32x4 yv = *(const u32x4*)(YA + offy + (size_t)bj * 8 * SEQ * 16), zv = *(const u32x4*)(SZ + off + bj * HALF);
;                     const i32x4 q0 = __builtin_bit_cast(i32x4, acc[ai][bj][m][0]), q1 = __builtin_bit_cast(i32x4, acc[ai][bj][m][1]);
;                     const f32x4 g0 = (f32x4){(float)q0[0], (float)q0[1], (float)q0[2], (float)q0[3]} * GATE_DEQ + bv[bj][0], g1 = (f32x4){(float)q1[0], (float)q1[1], (float)q1[2], (float)q1[3]} * GATE_DEQ + bv[bj][1];
;                     float o[8];
;                     o[0] = bf_lo(yv.x) * bf_lo(zv.x) * fast_sigmoid(g0[0]); o[1] = bf_hi(yv.x) * bf_hi(zv.x) * fast_sigmoid(g0[1]);
;                     o[2] = bf_lo(yv.y) * bf_lo(zv.y) * fast_sigmoid(g0[2]); o[3] = bf_hi(yv.y) * bf_hi(zv.y) * fast_sigmoid(g0[3]);
;                     o[4] = bf_lo(yv.z) * bf_lo(zv.z) * fast_sigmoid(g1[0]); o[5] = bf_hi(yv.z) * bf_hi(zv.z) * fast_sigmoid(g1[1]);
;                     o[6] = bf_lo(yv.w) * bf_lo(zv.w) * fast_sigmoid(g1[2]); o[7] = bf_hi(yv.w) * bf_hi(zv.w) * fast_sigmoid(g1[3]);
;                     u32x4 w; w.x = cvt_pk_bf16(o[0], o[1]); w.y = cvt_pk_bf16(o[2], o[3]); w.z = cvt_pk_bf16(o[4], o[5]); w.w = cvt_pk_bf16(o[6], o[7]);
;                     *(u32x4*)(V + off + bj * HALF) = w; } }
	v_lshlrev_b32_e32 v168, 16, v172
	v_and_b32_e32 v169, 0xffff0000, v172
	v_lshlrev_b32_e32 v188, 16, v180
	v_and_b32_e32 v189, 0xffff0000, v180
	v_pk_mul_f32 v[168:169], v[168:169], v[188:189]
	v_pk_mul_f32 v[116:117], v[168:169], v[116:117]
	v_lshlrev_b32_e32 v170, 16, v173
	v_and_b32_e32 v171, 0xffff0000, v173
	v_lshlrev_b32_e32 v190, 16, v181
	v_and_b32_e32 v191, 0xffff0000, v181
	v_pk_mul_f32 v[170:171], v[170:171], v[190:191]
	v_pk_mul_f32 v[118:119], v[170:171], v[118:119]
	v_lshlrev_b32_e32 v168, 16, v174
	v_and_b32_e32 v169, 0xffff0000, v174
	v_lshlrev_b32_e32 v188, 16, v182
	v_and_b32_e32 v189, 0xffff0000, v182
	v_pk_mul_f32 v[168:169], v[168:169], v[188:189]
	v_pk_mul_f32 v[112:113], v[168:169], v[112:113]
	v_lshlrev_b32_e32 v170, 16, v175
	v_and_b32_e32 v171, 0xffff0000, v175
	v_lshlrev_b32_e32 v190, 16, v183
	v_and_b32_e32 v191, 0xffff0000, v183
	v_pk_mul_f32 v[170:171], v[170:171], v[190:191]
	v_pk_mul_f32 v[114:115], v[170:171], v[114:115]
	global_load_dwordx4 v[180:183], v239, s[98:99] offset:256
	global_load_dwordx4 v[172:175], v185, s[10:11] offset:2048
	v_cvt_pk_bf16_f32 v116, v116, v117
	v_cvt_pk_bf16_f32 v117, v118, v119
	v_cvt_pk_bf16_f32 v118, v112, v113
	v_cvt_pk_bf16_f32 v119, v114, v115
	global_store_dwordx4 v239, v[116:119], s[100:101] offset:256
	v_cvt_f32_i32_e32 v108, v108
	v_cvt_f32_i32_e32 v109, v109
	v_cvt_f32_i32_e32 v110, v110
	v_cvt_f32_i32_e32 v111, v111
	v_cvt_f32_i32_e32 v104, v104
	v_cvt_f32_i32_e32 v105, v105
	v_cvt_f32_i32_e32 v106, v106
	v_cvt_f32_i32_e32 v107, v107
	v_pk_fma_f32 v[108:109], v[186:187], v[108:109], v[68:69] op_sel_hi:[0,1,1]
	v_pk_fma_f32 v[110:111], v[186:187], v[110:111], v[70:71] op_sel_hi:[0,1,1]
	v_pk_fma_f32 v[104:105], v[186:187], v[104:105], v[64:65] op_sel_hi:[0,1,1]
	v_pk_fma_f32 v[106:107], v[186:187], v[106:107], v[66:67] op_sel_hi:[0,1,1]
	v_pk_mul_f32 v[108:109], v[108:109], s[32:33] op_sel_hi:[1,0]
	v_pk_mul_f32 v[110:111], v[110:111], s[32:33] op_sel_hi:[1,0]
	v_pk_mul_f32 v[104:105], v[104:105], s[32:33] op_sel_hi:[1,0]
	v_pk_mul_f32 v[106:107], v[106:107], s[32:33] op_sel_hi:[1,0]
	v_exp_f32_e32 v108, v108
	v_exp_f32_e32 v109, v109
	v_exp_f32_e32 v110, v110
	v_exp_f32_e32 v111, v111
	v_exp_f32_e32 v104, v104
	v_exp_f32_e32 v105, v105
	v_exp_f32_e32 v106, v106
	v_exp_f32_e32 v107, v107
	v_pk_add_f32 v[108:109], v[108:109], 1.0 op_sel_hi:[1,0]
	v_pk_add_f32 v[110:111], v[110:111], 1.0 op_sel_hi:[1,0]
	v_pk_add_f32 v[104:105], v[104:105], 1.0 op_sel_hi:[1,0]
	v_pk_add_f32 v[106:107], v[106:107], 1.0 op_sel_hi:[1,0]
	v_rcp_f32_e32 v108, v108
	v_rcp_f32_e32 v109, v109
	v_rcp_f32_e32 v110, v110
	v_rcp_f32_e32 v111, v111
	v_rcp_f32_e32 v104, v104
	v_rcp_f32_e32 v105, v105
	v_rcp_f32_e32 v106, v106
	v_rcp_f32_e32 v107, v107
	s_waitcnt vmcnt(14)
	v_lshlrev_b32_e32 v168, 16, v240
	v_and_b32_e32 v169, 0xffff0000, v240
	v_lshlrev_b32_e32 v188, 16, v244
	v_and_b32_e32 v189, 0xffff0000, v244
	v_pk_mul_f32 v[168:169], v[168:169], v[188:189]
	v_pk_mul_f32 v[108:109], v[168:169], v[108:109]
	v_lshlrev_b32_e32 v170, 16, v241
	v_and_b32_e32 v171, 0xffff0000, v241
	v_lshlrev_b32_e32 v190, 16, v245
	v_and_b32_e32 v191, 0xffff0000, v245
	v_pk_mul_f32 v[170:171], v[170:171], v[190:191]
	v_pk_mul_f32 v[110:111], v[170:171], v[110:111]
	v_lshlrev_b32_e32 v168, 16, v242
	v_and_b32_e32 v169, 0xffff0000, v242
	v_lshlrev_b32_e32 v188, 16, v246
	v_and_b32_e32 v189, 0xffff0000, v246
	v_pk_mul_f32 v[168:169], v[168:169], v[188:189]
	v_pk_mul_f32 v[104:105], v[168:169], v[104:105]
	v_lshlrev_b32_e32 v170, 16, v243
	v_and_b32_e32 v171, 0xffff0000, v243
	v_lshlrev_b32_e32 v190, 16, v247
	v_and_b32_e32 v191, 0xffff0000, v247
	v_pk_mul_f32 v[170:171], v[170:171], v[190:191]
	v_pk_mul_f32 v[106:107], v[170:171], v[106:107]
	s_add_u32 s98, s12, 0x240000
	s_addc_u32 s99, s13, 0
	global_load_dwordx4 v[244:247], v239, s[98:99]
	global_load_dwordx4 v[240:243], v184, s[10:11] offset:2560
	v_cvt_pk_bf16_f32 v108, v108, v109
	v_cvt_pk_bf16_f32 v109, v110, v111
	v_cvt_pk_bf16_f32 v110, v104, v105
	v_cvt_pk_bf16_f32 v111, v106, v107
	s_add_u32 s100, s16, 0x80000
	s_addc_u32 s101, s17, 0
	global_store_dwordx4 v239, v[108:111], s[100:101]
	v_cvt_f32_i32_e32 v100, v100
	v_cvt_f32_i32_e32 v101, v101
	v_cvt_f32_i32_e32 v102, v102
	v_cvt_f32_i32_e32 v103, v103
	v_cvt_f32_i32_e32 v96, v96
	v_cvt_f32_i32_e32 v97, v97
	v_cvt_f32_i32_e32 v98, v98
	v_cvt_f32_i32_e32 v99, v99
	v_pk_fma_f32 v[100:101], v[186:187], v[100:101], v[136:137] op_sel_hi:[0,1,1]
	v_pk_fma_f32 v[102:103], v[186:187], v[102:103], v[138:139] op_sel_hi:[0,1,1]
	v_pk_fma_f32 v[96:97], v[186:187], v[96:97], v[140:141] op_sel_hi:[0,1,1]
	v_pk_fma_f32 v[98:99], v[186:187], v[98:99], v[142:143] op_sel_hi:[0,1,1]
	v_pk_mul_f32 v[100:101], v[100:101], s[32:33] op_sel_hi:[1,0]
	v_pk_mul_f32 v[102:103], v[102:103], s[32:33] op_sel_hi:[1,0]
	v_pk_mul_f32 v[96:97], v[96:97], s[32:33] op_sel_hi:[1,0]
	v_pk_mul_f32 v[98:99], v[98:99], s[32:33] op_sel_hi:[1,0]
	v_exp_f32_e32 v100, v100
	v_exp_f32_e32 v101, v101
	v_exp_f32_e32 v102, v102
	v_exp_f32_e32 v103, v103
	v_exp_f32_e32 v96, v96
	v_exp_f32_e32 v97, v97
	v_exp_f32_e32 v98, v98
	v_exp_f32_e32 v99, v99
	v_pk_add_f32 v[100:101], v[100:101], 1.0 op_sel_hi:[1,0]
	v_pk_add_f32 v[102:103], v[102:103], 1.0 op_sel_hi:[1,0]
	v_pk_add_f32 v[96:97], v[96:97], 1.0 op_sel_hi:[1,0]
	v_pk_add_f32 v[98:99], v[98:99], 1.0 op_sel_hi:[1,0]
	v_rcp_f32_e32 v100, v100
	v_rcp_f32_e32 v101, v101
	v_rcp_f32_e32 v102, v102
	v_rcp_f32_e32 v103, v103
	v_rcp_f32_e32 v96, v96
	v_rcp_f32_e32 v97, v97
	v_rcp_f32_e32 v98, v98
	v_rcp_f32_e32 v99, v99
	s_waitcnt vmcnt(15)
; __device__ __forceinline__ unsigned cvt_pk_bf16(float lo, float hi) { unsigned r; asm volatile("v_cvt_pk_bf16_f32 %0, %1, %2" : "=v"(r) : "v"(lo), "v"(hi)); return r; }
; __device__ __forceinline__ float bf_lo(unsigned w) { return __uint_as_float(w << 16); }
; __device__ __forceinline__ float bf_hi(unsigned w) { return __uint_as_float(w & 0xffff0000u); }
; __device__ __forceinline__ float fast_sigmoid(float x) { return __builtin_amdgcn_rcpf(1.0f + __builtin_amdgcn_exp2f(-1.4426950408889634f * x)); }
;     __device__ __forceinline__ void operator()(const f32x4 (&acc)[2][2][4][2], const Unit& u, int wr, int wc, int fr, int fq) const {
;     ...
;             for (int m = 0; m < 4; ++m) { const int row = row0 + ai * HALF + m * 16; const size_t off = (size_t)row * EI + col0;
;                 const size_t offy = ((size_t)((row >> 13) * NG + (col0 >> 4)) * SEQ + (row & (SEQ - 1))) * 16 + (col0 & 15);
; #pragma unroll
;                 for (int bj = 0; bj < 2; ++bj) { const u32x4 yv = *(const u32x4*)(YA + offy + (size_t)bj * 8 * SEQ * 16), zv = *(const u32x4*)(SZ + off + bj * HALF);
;                     const i32x4 q0 = __builtin_bit_cast(i32x4, acc[ai][bj][m][0]), q1 = __builtin_bit_cast(i32x4, acc[ai][bj][m][1]);
;                     const f32x4 g0 = (f32x4){(float)q0[0], (float)q0[1], (float)q0[2], (float)q0[3]} * GATE_DEQ + bv[bj][0], g1 = (f32x4){(float)q1[0], (float)q1[1], (float)q1[2], (float)q1[3]} * GATE_DEQ + bv[bj][1];
;                     float o[8];
;                     o[0] = bf_lo(yv.x) * bf_lo(zv.x) * fast_sigmoid(g0[0]); o[1] = bf_hi(yv.x) * bf_hi(zv.x) * fast_sigmoid(g0[1]);
;                     o[2] = bf_lo(yv.y) * bf_lo(zv.y) * fast_sigmoid(g0[2]); o[3] = bf_hi(yv.y) * bf_hi(zv.y) * fast_sigmoid(g0[3]);
;                     o[4] = bf_lo(yv.z) * bf_lo(zv.z) * fast_sigmoid(g1[0]); o[5] = bf_hi(yv.z) * bf_hi(zv.z) * fast_sigmoid(g1[1]);
;                     o[6] = bf_lo(yv.w) * bf_lo(zv.w) * fast_sigmoid(g1[2]); o[7] = bf_hi(yv.w) * bf_hi(zv.w) * fast_sigmoid(g1[3]);
;                     u32x4 w; w.x = cvt_pk_bf16(o[0], o[1]); w.y = cvt_pk_bf16(o[2], o[3]); w.z = cvt_pk_bf16(o[4], o[5]); w.w = cvt_pk_bf16(o[6], o[7]);
;                     *(u32x4*)(V + off + bj * HALF) = w; } }
	v_lshlrev_b32_e32 v168, 16, v248
	v_and_b32_e32 v169, 0xffff0000, v248
	v_lshlrev_b32_e32 v188, 16, v176
	v_and_b32_e32 v189, 0xffff0000, v176
	v_pk_mul_f32 v[168:169], v[168:169], v[188:189]
	v_pk_mul_f32 v[100:101], v[168:169], v[100:101]
	v_lshlrev_b32_e32 v170, 16, v249
	v_and_b32_e32 v171, 0xffff0000, v249
	v_lshlrev_b32_e32 v190, 16, v177
	v_and_b32_e32 v191, 0xffff0000, v177
	v_pk_mul_f32 v[170:171], v[170:171], v[190:191]
	v_pk_mul_f32 v[102:103], v[170:171], v[102:103]
	v_lshlrev_b32_e32 v168, 16, v250
	v_and_b32_e32 v169, 0xffff0000, v250
	v_lshlrev_b32_e32 v188, 16, v178
	v_and_b32_e32 v189, 0xffff0000, v178
	v_pk_mul_f32 v[168:169], v[168:169], v[188:189]
	v_pk_mul_f32 v[96:97], v[168:169], v[96:97]
	v_lshlrev_b32_e32 v170, 16, v251
	v_and_b32_e32 v171, 0xffff0000, v251
	v_lshlrev_b32_e32 v190, 16, v179
	v_and_b32_e32 v191, 0xffff0000, v179
	v_pk_mul_f32 v[170:171], v[170:171], v[190:191]
	v_pk_mul_f32 v[98:99], v[170:171], v[98:99]
	global_load_dwordx4 v[176:179], v239, s[98:99] offset:256
	global_load_dwordx4 v[248:251], v185, s[10:11] offset:2560
	v_cvt_pk_bf16_f32 v100, v100, v101
	v_cvt_pk_bf16_f32 v101, v102, v103
	v_cvt_pk_bf16_f32 v102, v96, v97
	v_cvt_pk_bf16_f32 v103, v98, v99
	global_store_dwordx4 v239, v[100:103], s[100:101] offset:256
	v_cvt_f32_i32_e32 v92, v92
	v_cvt_f32_i32_e32 v93, v93
	v_cvt_f32_i32_e32 v94, v94
	v_cvt_f32_i32_e32 v95, v95
	v_cvt_f32_i32_e32 v88, v88
	v_cvt_f32_i32_e32 v89, v89
	v_cvt_f32_i32_e32 v90, v90
	v_cvt_f32_i32_e32 v91, v91
	v_pk_fma_f32 v[92:93], v[186:187], v[92:93], v[68:69] op_sel_hi:[0,1,1]
	v_pk_fma_f32 v[94:95], v[186:187], v[94:95], v[70:71] op_sel_hi:[0,1,1]
	v_pk_fma_f32 v[88:89], v[186:187], v[88:89], v[64:65] op_sel_hi:[0,1,1]
	v_pk_fma_f32 v[90:91], v[186:187], v[90:91], v[66:67] op_sel_hi:[0,1,1]
	v_pk_mul_f32 v[92:93], v[92:93], s[32:33] op_sel_hi:[1,0]
	v_pk_mul_f32 v[94:95], v[94:95], s[32:33] op_sel_hi:[1,0]
	v_pk_mul_f32 v[88:89], v[88:89], s[32:33] op_sel_hi:[1,0]
	v_pk_mul_f32 v[90:91], v[90:91], s[32:33] op_sel_hi:[1,0]
	v_exp_f32_e32 v92, v92
	v_exp_f32_e32 v93, v93
	v_exp_f32_e32 v94, v94
	v_exp_f32_e32 v95, v95
	v_exp_f32_e32 v88, v88
	v_exp_f32_e32 v89, v89
	v_exp_f32_e32 v90, v90
	v_exp_f32_e32 v91, v91
	v_pk_add_f32 v[92:93], v[92:93], 1.0 op_sel_hi:[1,0]
	v_pk_add_f32 v[94:95], v[94:95], 1.0 op_sel_hi:[1,0]
	v_pk_add_f32 v[88:89], v[88:89], 1.0 op_sel_hi:[1,0]
	v_pk_add_f32 v[90:91], v[90:91], 1.0 op_sel_hi:[1,0]
	v_rcp_f32_e32 v92, v92
	v_rcp_f32_e32 v93, v93
	v_rcp_f32_e32 v94, v94
	v_rcp_f32_e32 v95, v95
	v_rcp_f32_e32 v88, v88
	v_rcp_f32_e32 v89, v89
	v_rcp_f32_e32 v90, v90
	v_rcp_f32_e32 v91, v91
	s_waitcnt vmcnt(16)
	v_lshlrev_b32_e32 v168, 16, v144
	v_and_b32_e32 v169, 0xffff0000, v144
	v_lshlrev_b32_e32 v188, 16, v148
	v_and_b32_e32 v189, 0xffff0000, v148
	v_pk_mul_f32 v[168:169], v[168:169], v[188:189]
	v_pk_mul_f32 v[92:93], v[168:169], v[92:93]
	v_lshlrev_b32_e32 v170, 16, v145
	v_and_b32_e32 v171, 0xffff0000, v145
	v_lshlrev_b32_e32 v190, 16, v149
	v_and_b32_e32 v191, 0xffff0000, v149
	v_pk_mul_f32 v[170:171], v[170:171], v[190:191]
	v_pk_mul_f32 v[94:95], v[170:171], v[94:95]
	v_lshlrev_b32_e32 v168, 16, v146
	v_and_b32_e32 v169, 0xffff0000, v146
	v_lshlrev_b32_e32 v188, 16, v150
	v_and_b32_e32 v189, 0xffff0000, v150
	v_pk_mul_f32 v[168:169], v[168:169], v[188:189]
	v_pk_mul_f32 v[88:89], v[168:169], v[88:89]
	v_lshlrev_b32_e32 v170, 16, v147
	v_and_b32_e32 v171, 0xffff0000, v147
	v_lshlrev_b32_e32 v190, 16, v151
	v_and_b32_e32 v191, 0xffff0000, v151
	v_pk_mul_f32 v[170:171], v[170:171], v[190:191]
	v_pk_mul_f32 v[90:91], v[170:171], v[90:91]
	s_add_u32 s98, s12, 0x280000
	s_addc_u32 s99, s13, 0
	global_load_dwordx4 v[148:151], v239, s[98:99]
	global_load_dwordx4 v[144:147], v184, s[10:11] offset:3072
	v_cvt_pk_bf16_f32 v92, v92, v93
	v_cvt_pk_bf16_f32 v93, v94, v95
	v_cvt_pk_bf16_f32 v94, v88, v89
	v_cvt_pk_bf16_f32 v95, v90, v91
	s_add_u32 s100, s16, 0xc0000
	s_addc_u32 s101, s17, 0
	global_store_dwordx4 v239, v[92:95], s[100:101]
	v_cvt_f32_i32_e32 v84, v84
	v_cvt_f32_i32_e32 v85, v85
	v_cvt_f32_i32_e32 v86, v86
	v_cvt_f32_i32_e32 v87, v87
	v_cvt_f32_i32_e32 v80, v80
	v_cvt_f32_i32_e32 v81, v81
	v_cvt_f32_i32_e32 v82, v82
	v_cvt_f32_i32_e32 v83, v83
	v_pk_fma_f32 v[84:85], v[186:187], v[84:85], v[136:137] op_sel_hi:[0,1,1]
	v_pk_fma_f32 v[86:87], v[186:187], v[86:87], v[138:139] op_sel_hi:[0,1,1]
	v_pk_fma_f32 v[80:81], v[186:187], v[80:81], v[140:141] op_sel_hi:[0,1,1]
	v_pk_fma_f32 v[82:83], v[186:187], v[82:83], v[142:143] op_sel_hi:[0,1,1]
	v_pk_mul_f32 v[84:85], v[84:85], s[32:33] op_sel_hi:[1,0]
	v_pk_mul_f32 v[86:87], v[86:87], s[32:33] op_sel_hi:[1,0]
	v_pk_mul_f32 v[80:81], v[80:81], s[32:33] op_sel_hi:[1,0]
	v_pk_mul_f32 v[82:83], v[82:83], s[32:33] op_sel_hi:[1,0]
	v_exp_f32_e32 v84, v84
	v_exp_f32_e32 v85, v85
	v_exp_f32_e32 v86, v86
	v_exp_f32_e32 v87, v87
	v_exp_f32_e32 v80, v80
	v_exp_f32_e32 v81, v81
	v_exp_f32_e32 v82, v82
	v_exp_f32_e32 v83, v83
	v_pk_add_f32 v[84:85], v[84:85], 1.0 op_sel_hi:[1,0]
	v_pk_add_f32 v[86:87], v[86:87], 1.0 op_sel_hi:[1,0]
	v_pk_add_f32 v[80:81], v[80:81], 1.0 op_sel_hi:[1,0]
	v_pk_add_f32 v[82:83], v[82:83], 1.0 op_sel_hi:[1,0]
	v_rcp_f32_e32 v84, v84
	v_rcp_f32_e32 v85, v85
	v_rcp_f32_e32 v86, v86
	v_rcp_f32_e32 v87, v87
	v_rcp_f32_e32 v80, v80
	v_rcp_f32_e32 v81, v81
	v_rcp_f32_e32 v82, v82
	v_rcp_f32_e32 v83, v83
	s_waitcnt vmcnt(16)
; __device__ __forceinline__ unsigned cvt_pk_bf16(float lo, float hi) { unsigned r; asm volatile("v_cvt_pk_bf16_f32 %0, %1, %2" : "=v"(r) : "v"(lo), "v"(hi)); return r; }
; __device__ __forceinline__ float bf_lo(unsigned w) { return __uint_as_float(w << 16); }
; __device__ __forceinline__ float bf_hi(unsigned w) { return __uint_as_float(w & 0xffff0000u); }
; __device__ __forceinline__ float fast_sigmoid(float x) { return __builtin_amdgcn_rcpf(1.0f + __builtin_amdgcn_exp2f(-1.4426950408889634f * x)); }
;     __device__ __forceinline__ void operator()(const f32x4 (&acc)[2][2][4][2], const Unit& u, int wr, int wc, int fr, int fq) const {
;     ...
;             for (int m = 0; m < 4; ++m) { const int row = row0 + ai * HALF + m * 16; const size_t off = (size_t)row * EI + col0;
;                 const size_t offy = ((size_t)((row >> 13) * NG + (col0 >> 4)) * SEQ + (row & (SEQ - 1))) * 16 + (col0 & 15);
; #pragma unroll
;                 for (int bj = 0; bj < 2; ++bj) { const u32x4 yv = *(const u32x4*)(YA + offy + (size_t)bj * 8 * SEQ * 16), zv = *(const u32x4*)(SZ + off + bj * HALF);
;                     const i32x4 q0 = __builtin_bit_cast(i32x4, acc[ai][bj][m][0]), q1 = __builtin_bit_cast(i32x4, acc[ai][bj][m][1]);
;                     const f32x4 g0 = (f32x4){(float)q0[0], (float)q0[1], (float)q0[2], (float)q0[3]} * GATE_DEQ + bv[bj][0], g1 = (f32x4){(float)q1[0], (float)q1[1], (float)q1[2], (float)q1[3]} * GATE_DEQ + bv[bj][1];
;                     float o[8];
;                     o[0] = bf_lo(yv.x) * bf_lo(zv.x) * fast_sigmoid(g0[0]); o[1] = bf_hi(yv.x) * bf_hi(zv.x) * fast_sigmoid(g0[1]);
;                     o[2] = bf_lo(yv.y) * bf_lo(zv.y) * fast_sigmoid(g0[2]); o[3] = bf_hi(yv.y) * bf_hi(zv.y) * fast_sigmoid(g0[3]);
;                     o[4] = bf_lo(yv.z) * bf_lo(zv.z) * fast_sigmoid(g1[0]); o[5] = bf_hi(yv.z) * bf_hi(zv.z) * fast_sigmoid(g1[1]);
;                     o[6] = bf_lo(yv.w) * bf_lo(zv.w) * fast_sigmoid(g1[2]); o[7] = bf_hi(yv.w) * bf_hi(zv.w) * fast_sigmoid(g1[3]);
;                     u32x4 w; w.x = cvt_pk_bf16(o[0], o[1]); w.y = cvt_pk_bf16(o[2], o[3]); w.z = cvt_pk_bf16(o[4], o[5]); w.w = cvt_pk_bf16(o[6], o[7]);
;                     *(u32x4*)(V + off + bj * HALF) = w; } }
	v_lshlrev_b32_e32 v168, 16, v152
	v_and_b32_e32 v169, 0xffff0000, v152
	v_lshlrev_b32_e32 v188, 16, v156
	v_and_b32_e32 v189, 0xffff0000, v156
	v_pk_mul_f32 v[168:169], v[168:169], v[188:189]
	v_pk_mul_f32 v[84:85], v[168:169], v[84:85]
	v_lshlrev_b32_e32 v170, 16, v153
	v_and_b32_e32 v171, 0xffff0000, v153
	v_lshlrev_b32_e32 v190, 16, v157
	v_and_b32_e32 v191, 0xffff0000, v157
	v_pk_mul_f32 v[170:171], v[170:171], v[190:191]
	v_pk_mul_f32 v[86:87], v[170:171], v[86:87]
	v_lshlrev_b32_e32 v168, 16, v154
	v_and_b32_e32 v169, 0xffff0000, v154
	v_lshlrev_b32_e32 v188, 16, v158
	v_and_b32_e32 v189, 0xffff0000, v158
	v_pk_mul_f32 v[168:169], v[168:169], v[188:189]
	v_pk_mul_f32 v[80:81], v[168:169], v[80:81]
	v_lshlrev_b32_e32 v170, 16, v155
	v_and_b32_e32 v171, 0xffff0000, v155
	v_lshlrev_b32_e32 v190, 16, v159
	v_and_b32_e32 v191, 0xffff0000, v159
	v_pk_mul_f32 v[170:171], v[170:171], v[190:191]
	v_pk_mul_f32 v[82:83], v[170:171], v[82:83]
	global_load_dwordx4 v[156:159], v239, s[98:99] offset:256
	global_load_dwordx4 v[152:155], v185, s[10:11] offset:3072
	v_cvt_pk_bf16_f32 v84, v84, v85
	v_cvt_pk_bf16_f32 v85, v86, v87
	v_cvt_pk_bf16_f32 v86, v80, v81
	v_cvt_pk_bf16_f32 v87, v82, v83
	global_store_dwordx4 v239, v[84:87], s[100:101] offset:256
	v_cvt_f32_i32_e32 v76, v76
	v_cvt_f32_i32_e32 v77, v77
	v_cvt_f32_i32_e32 v78, v78
	v_cvt_f32_i32_e32 v79, v79
	v_cvt_f32_i32_e32 v72, v72
	v_cvt_f32_i32_e32 v73, v73
	v_cvt_f32_i32_e32 v74, v74
	v_cvt_f32_i32_e32 v75, v75
	v_pk_fma_f32 v[76:77], v[186:187], v[76:77], v[68:69] op_sel_hi:[0,1,1]
	v_pk_fma_f32 v[78:79], v[186:187], v[78:79], v[70:71] op_sel_hi:[0,1,1]
	v_pk_fma_f32 v[72:73], v[186:187], v[72:73], v[64:65] op_sel_hi:[0,1,1]
	v_pk_fma_f32 v[74:75], v[186:187], v[74:75], v[66:67] op_sel_hi:[0,1,1]
	v_pk_mul_f32 v[76:77], v[76:77], s[32:33] op_sel_hi:[1,0]
	v_pk_mul_f32 v[78:79], v[78:79], s[32:33] op_sel_hi:[1,0]
	v_pk_mul_f32 v[72:73], v[72:73], s[32:33] op_sel_hi:[1,0]
	v_pk_mul_f32 v[74:75], v[74:75], s[32:33] op_sel_hi:[1,0]
	v_exp_f32_e32 v76, v76
	v_exp_f32_e32 v77, v77
	v_exp_f32_e32 v78, v78
	v_exp_f32_e32 v79, v79
	v_exp_f32_e32 v72, v72
	v_exp_f32_e32 v73, v73
	v_exp_f32_e32 v74, v74
	v_exp_f32_e32 v75, v75
	v_pk_add_f32 v[76:77], v[76:77], 1.0 op_sel_hi:[1,0]
	v_pk_add_f32 v[78:79], v[78:79], 1.0 op_sel_hi:[1,0]
	v_pk_add_f32 v[72:73], v[72:73], 1.0 op_sel_hi:[1,0]
	v_pk_add_f32 v[74:75], v[74:75], 1.0 op_sel_hi:[1,0]
	v_rcp_f32_e32 v76, v76
	v_rcp_f32_e32 v77, v77
	v_rcp_f32_e32 v78, v78
	v_rcp_f32_e32 v79, v79
	v_rcp_f32_e32 v72, v72
	v_rcp_f32_e32 v73, v73
	v_rcp_f32_e32 v74, v74
	v_rcp_f32_e32 v75, v75
	s_waitcnt vmcnt(16)
	v_lshlrev_b32_e32 v168, 16, v160
	v_and_b32_e32 v169, 0xffff0000, v160
	v_lshlrev_b32_e32 v188, 16, v164
	v_and_b32_e32 v189, 0xffff0000, v164
	v_pk_mul_f32 v[168:169], v[168:169], v[188:189]
	v_pk_mul_f32 v[76:77], v[168:169], v[76:77]
	v_lshlrev_b32_e32 v170, 16, v161
	v_and_b32_e32 v171, 0xffff0000, v161
	v_lshlrev_b32_e32 v190, 16, v165
	v_and_b32_e32 v191, 0xffff0000, v165
	v_pk_mul_f32 v[170:171], v[170:171], v[190:191]
	v_pk_mul_f32 v[78:79], v[170:171], v[78:79]
	v_lshlrev_b32_e32 v168, 16, v162
	v_and_b32_e32 v169, 0xffff0000, v162
	v_lshlrev_b32_e32 v188, 16, v166
	v_and_b32_e32 v189, 0xffff0000, v166
	v_pk_mul_f32 v[168:169], v[168:169], v[188:189]
	v_pk_mul_f32 v[72:73], v[168:169], v[72:73]
	v_lshlrev_b32_e32 v170, 16, v163
	v_and_b32_e32 v171, 0xffff0000, v163
	v_lshlrev_b32_e32 v190, 16, v167
	v_and_b32_e32 v191, 0xffff0000, v167
	v_pk_mul_f32 v[170:171], v[170:171], v[190:191]
	v_pk_mul_f32 v[74:75], v[170:171], v[74:75]
	s_add_u32 s98, s12, 0x2c0000
	s_addc_u32 s99, s13, 0
	global_load_dwordx4 v[164:167], v239, s[98:99]
	global_load_dwordx4 v[160:163], v184, s[10:11] offset:3584
	v_cvt_pk_bf16_f32 v76, v76, v77
	v_cvt_pk_bf16_f32 v77, v78, v79
	v_cvt_pk_bf16_f32 v78, v72, v73
	v_cvt_pk_bf16_f32 v79, v74, v75
	s_add_u32 s100, s16, 0x200000
	s_addc_u32 s101, s17, 0
	global_store_dwordx4 v239, v[76:79], s[100:101]
	v_cvt_f32_i32_e32 v52, v52
	v_cvt_f32_i32_e32 v53, v53
	v_cvt_f32_i32_e32 v54, v54
	v_cvt_f32_i32_e32 v55, v55
	v_cvt_f32_i32_e32 v48, v48
	v_cvt_f32_i32_e32 v49, v49
	v_cvt_f32_i32_e32 v50, v50
	v_cvt_f32_i32_e32 v51, v51
	v_pk_fma_f32 v[52:53], v[186:187], v[52:53], v[136:137] op_sel_hi:[0,1,1]
	v_pk_fma_f32 v[54:55], v[186:187], v[54:55], v[138:139] op_sel_hi:[0,1,1]
	v_pk_fma_f32 v[48:49], v[186:187], v[48:49], v[140:141] op_sel_hi:[0,1,1]
	v_pk_fma_f32 v[50:51], v[186:187], v[50:51], v[142:143] op_sel_hi:[0,1,1]
	v_pk_mul_f32 v[52:53], v[52:53], s[32:33] op_sel_hi:[1,0]
	v_pk_mul_f32 v[54:55], v[54:55], s[32:33] op_sel_hi:[1,0]
	v_pk_mul_f32 v[48:49], v[48:49], s[32:33] op_sel_hi:[1,0]
	v_pk_mul_f32 v[50:51], v[50:51], s[32:33] op_sel_hi:[1,0]
	v_exp_f32_e32 v52, v52
	v_exp_f32_e32 v53, v53
	v_exp_f32_e32 v54, v54
	v_exp_f32_e32 v55, v55
	v_exp_f32_e32 v48, v48
	v_exp_f32_e32 v49, v49
	v_exp_f32_e32 v50, v50
	v_exp_f32_e32 v51, v51
	v_pk_add_f32 v[52:53], v[52:53], 1.0 op_sel_hi:[1,0]
	v_pk_add_f32 v[54:55], v[54:55], 1.0 op_sel_hi:[1,0]
	v_pk_add_f32 v[48:49], v[48:49], 1.0 op_sel_hi:[1,0]
	v_pk_add_f32 v[50:51], v[50:51], 1.0 op_sel_hi:[1,0]
	v_rcp_f32_e32 v52, v52
	v_rcp_f32_e32 v53, v53
	v_rcp_f32_e32 v54, v54
	v_rcp_f32_e32 v55, v55
	v_rcp_f32_e32 v48, v48
	v_rcp_f32_e32 v49, v49
	v_rcp_f32_e32 v50, v50
	v_rcp_f32_e32 v51, v51
	s_waitcnt vmcnt(16)
; __device__ __forceinline__ unsigned cvt_pk_bf16(float lo, float hi) { unsigned r; asm volatile("v_cvt_pk_bf16_f32 %0, %1, %2" : "=v"(r) : "v"(lo), "v"(hi)); return r; }
; __device__ __forceinline__ float bf_lo(unsigned w) { return __uint_as_float(w << 16); }
; __device__ __forceinline__ float bf_hi(unsigned w) { return __uint_as_float(w & 0xffff0000u); }
; __device__ __forceinline__ float fast_sigmoid(float x) { return __builtin_amdgcn_rcpf(1.0f + __builtin_amdgcn_exp2f(-1.4426950408889634f * x)); }
;     __device__ __forceinline__ void operator()(const f32x4 (&acc)[2][2][4][2], const Unit& u, int wr, int wc, int fr, int fq) const {
;     ...
;             for (int m = 0; m < 4; ++m) { const int row = row0 + ai * HALF + m * 16; const size_t off = (size_t)row * EI + col0;
;                 const size_t offy = ((size_t)((row >> 13) * NG + (col0 >> 4)) * SEQ + (row & (SEQ - 1))) * 16 + (col0 & 15);
; #pragma unroll
;                 for (int bj = 0; bj < 2; ++bj) { const u32x4 yv = *(const u32x4*)(YA + offy + (size_t)bj * 8 * SEQ * 16), zv = *(const u32x4*)(SZ + off + bj * HALF);
;                     const i32x4 q0 = __builtin_bit_cast(i32x4, acc[ai][bj][m][0]), q1 = __builtin_bit_cast(i32x4, acc[ai][bj][m][1]);
;                     const f32x4 g0 = (f32x4){(float)q0[0], (float)q0[1], (float)q0[2], (float)q0[3]} * GATE_DEQ + bv[bj][0], g1 = (f32x4){(float)q1[0], (float)q1[1], (float)q1[2], (float)q1[3]} * GATE_DEQ + bv[bj][1];
;                     float o[8];
;                     o[0] = bf_lo(yv.x) * bf_lo(zv.x) * fast_sigmoid(g0[0]); o[1] = bf_hi(yv.x) * bf_hi(zv.x) * fast_sigmoid(g0[1]);
;                     o[2] = bf_lo(yv.y) * bf_lo(zv.y) * fast_sigmoid(g0[2]); o[3] = bf_hi(yv.y) * bf_hi(zv.y) * fast_sigmoid(g0[3]);
;                     o[4] = bf_lo(yv.z) * bf_lo(zv.z) * fast_sigmoid(g1[0]); o[5] = bf_hi(yv.z) * bf_hi(zv.z) * fast_sigmoid(g1[1]);
;                     o[6] = bf_lo(yv.w) * bf_lo(zv.w) * fast_sigmoid(g1[2]); o[7] = bf_hi(yv.w) * bf_hi(zv.w) * fast_sigmoid(g1[3]);
;                     u32x4 w; w.x = cvt_pk_bf16(o[0], o[1]); w.y = cvt_pk_bf16(o[2], o[3]); w.z = cvt_pk_bf16(o[4], o[5]); w.w = cvt_pk_bf16(o[6], o[7]);
;                     *(u32x4*)(V + off + bj * HALF) = w; } }
	v_lshlrev_b32_e32 v168, 16, v172
	v_and_b32_e32 v169, 0xffff0000, v172
	v_lshlrev_b32_e32 v188, 16, v180
	v_and_b32_e32 v189, 0xffff0000, v180
	v_pk_mul_f32 v[168:169], v[168:169], v[188:189]
	v_pk_mul_f32 v[52:53], v[168:169], v[52:53]
	v_lshlrev_b32_e32 v170, 16, v173
	v_and_b32_e32 v171, 0xffff0000, v173
	v_lshlrev_b32_e32 v190, 16, v181
	v_and_b32_e32 v191, 0xffff0000, v181
	v_pk_mul_f32 v[170:171], v[170:171], v[190:191]
	v_pk_mul_f32 v[54:55], v[170:171], v[54:55]
	v_lshlrev_b32_e32 v168, 16, v174
	v_and_b32_e32 v169, 0xffff0000, v174
	v_lshlrev_b32_e32 v188, 16, v182
	v_and_b32_e32 v189, 0xffff0000, v182
	v_pk_mul_f32 v[168:169], v[168:169], v[188:189]
	v_pk_mul_f32 v[48:49], v[168:169], v[48:49]
	v_lshlrev_b32_e32 v170, 16, v175
	v_and_b32_e32 v171, 0xffff0000, v175
	v_lshlrev_b32_e32 v190, 16, v183
	v_and_b32_e32 v191, 0xffff0000, v183
	v_pk_mul_f32 v[170:171], v[170:171], v[190:191]
	v_pk_mul_f32 v[50:51], v[170:171], v[50:51]
	global_load_dwordx4 v[180:183], v239, s[98:99] offset:256
	global_load_dwordx4 v[172:175], v185, s[10:11] offset:3584
	v_cvt_pk_bf16_f32 v52, v52, v53
	v_cvt_pk_bf16_f32 v53, v54, v55
	v_cvt_pk_bf16_f32 v54, v48, v49
	v_cvt_pk_bf16_f32 v55, v50, v51
	global_store_dwordx4 v239, v[52:55], s[100:101] offset:256
	v_cvt_f32_i32_e32 v44, v44
	v_cvt_f32_i32_e32 v45, v45
	v_cvt_f32_i32_e32 v46, v46
	v_cvt_f32_i32_e32 v47, v47
	v_cvt_f32_i32_e32 v40, v40
	v_cvt_f32_i32_e32 v41, v41
	v_cvt_f32_i32_e32 v42, v42
	v_cvt_f32_i32_e32 v43, v43
	v_pk_fma_f32 v[44:45], v[186:187], v[44:45], v[68:69] op_sel_hi:[0,1,1]
	v_pk_fma_f32 v[46:47], v[186:187], v[46:47], v[70:71] op_sel_hi:[0,1,1]
	v_pk_fma_f32 v[40:41], v[186:187], v[40:41], v[64:65] op_sel_hi:[0,1,1]
	v_pk_fma_f32 v[42:43], v[186:187], v[42:43], v[66:67] op_sel_hi:[0,1,1]
	v_pk_mul_f32 v[44:45], v[44:45], s[32:33] op_sel_hi:[1,0]
	v_pk_mul_f32 v[46:47], v[46:47], s[32:33] op_sel_hi:[1,0]
	v_pk_mul_f32 v[40:41], v[40:41], s[32:33] op_sel_hi:[1,0]
	v_pk_mul_f32 v[42:43], v[42:43], s[32:33] op_sel_hi:[1,0]
	v_exp_f32_e32 v44, v44
	v_exp_f32_e32 v45, v45
	v_exp_f32_e32 v46, v46
	v_exp_f32_e32 v47, v47
	v_exp_f32_e32 v40, v40
	v_exp_f32_e32 v41, v41
	v_exp_f32_e32 v42, v42
	v_exp_f32_e32 v43, v43
	v_pk_add_f32 v[44:45], v[44:45], 1.0 op_sel_hi:[1,0]
	v_pk_add_f32 v[46:47], v[46:47], 1.0 op_sel_hi:[1,0]
	v_pk_add_f32 v[40:41], v[40:41], 1.0 op_sel_hi:[1,0]
	v_pk_add_f32 v[42:43], v[42:43], 1.0 op_sel_hi:[1,0]
	v_rcp_f32_e32 v44, v44
	v_rcp_f32_e32 v45, v45
	v_rcp_f32_e32 v46, v46
	v_rcp_f32_e32 v47, v47
	v_rcp_f32_e32 v40, v40
	v_rcp_f32_e32 v41, v41
	v_rcp_f32_e32 v42, v42
	v_rcp_f32_e32 v43, v43
	s_waitcnt vmcnt(16)
	v_lshlrev_b32_e32 v168, 16, v240
	v_and_b32_e32 v169, 0xffff0000, v240
	v_lshlrev_b32_e32 v188, 16, v244
	v_and_b32_e32 v189, 0xffff0000, v244
	v_pk_mul_f32 v[168:169], v[168:169], v[188:189]
	v_pk_mul_f32 v[44:45], v[168:169], v[44:45]
	v_lshlrev_b32_e32 v170, 16, v241
	v_and_b32_e32 v171, 0xffff0000, v241
	v_lshlrev_b32_e32 v190, 16, v245
	v_and_b32_e32 v191, 0xffff0000, v245
	v_pk_mul_f32 v[170:171], v[170:171], v[190:191]
	v_pk_mul_f32 v[46:47], v[170:171], v[46:47]
	v_lshlrev_b32_e32 v168, 16, v242
	v_and_b32_e32 v169, 0xffff0000, v242
	v_lshlrev_b32_e32 v188, 16, v246
	v_and_b32_e32 v189, 0xffff0000, v246
	v_pk_mul_f32 v[168:169], v[168:169], v[188:189]
	v_pk_mul_f32 v[40:41], v[168:169], v[40:41]
	v_lshlrev_b32_e32 v170, 16, v243
	v_and_b32_e32 v171, 0xffff0000, v243
	v_lshlrev_b32_e32 v190, 16, v247
	v_and_b32_e32 v191, 0xffff0000, v247
	v_pk_mul_f32 v[170:171], v[170:171], v[190:191]
	v_pk_mul_f32 v[42:43], v[170:171], v[42:43]
	v_cvt_pk_bf16_f32 v44, v44, v45
	v_cvt_pk_bf16_f32 v45, v46, v47
	v_cvt_pk_bf16_f32 v46, v40, v41
	v_cvt_pk_bf16_f32 v47, v42, v43
	s_add_u32 s100, s16, 0x240000
	s_addc_u32 s101, s17, 0
	global_store_dwordx4 v239, v[44:47], s[100:101]
	v_cvt_f32_i32_e32 v36, v36
	v_cvt_f32_i32_e32 v37, v37
	v_cvt_f32_i32_e32 v38, v38
	v_cvt_f32_i32_e32 v39, v39
	v_cvt_f32_i32_e32 v32, v32
	v_cvt_f32_i32_e32 v33, v33
	v_cvt_f32_i32_e32 v34, v34
	v_cvt_f32_i32_e32 v35, v35
	v_pk_fma_f32 v[36:37], v[186:187], v[36:37], v[136:137] op_sel_hi:[0,1,1]
	v_pk_fma_f32 v[38:39], v[186:187], v[38:39], v[138:139] op_sel_hi:[0,1,1]
	v_pk_fma_f32 v[32:33], v[186:187], v[32:33], v[140:141] op_sel_hi:[0,1,1]
	v_pk_fma_f32 v[34:35], v[186:187], v[34:35], v[142:143] op_sel_hi:[0,1,1]
	v_pk_mul_f32 v[36:37], v[36:37], s[32:33] op_sel_hi:[1,0]
	v_pk_mul_f32 v[38:39], v[38:39], s[32:33] op_sel_hi:[1,0]
	v_pk_mul_f32 v[32:33], v[32:33], s[32:33] op_sel_hi:[1,0]
	v_pk_mul_f32 v[34:35], v[34:35], s[32:33] op_sel_hi:[1,0]
	v_exp_f32_e32 v36, v36
	v_exp_f32_e32 v37, v37
	v_exp_f32_e32 v38, v38
	v_exp_f32_e32 v39, v39
	v_exp_f32_e32 v32, v32
	v_exp_f32_e32 v33, v33
	v_exp_f32_e32 v34, v34
	v_exp_f32_e32 v35, v35
	v_pk_add_f32 v[36:37], v[36:37], 1.0 op_sel_hi:[1,0]
	v_pk_add_f32 v[38:39], v[38:39], 1.0 op_sel_hi:[1,0]
	v_pk_add_f32 v[32:33], v[32:33], 1.0 op_sel_hi:[1,0]
	v_pk_add_f32 v[34:35], v[34:35], 1.0 op_sel_hi:[1,0]
	v_rcp_f32_e32 v36, v36
	v_rcp_f32_e32 v37, v37
	v_rcp_f32_e32 v38, v38
	v_rcp_f32_e32 v39, v39
	v_rcp_f32_e32 v32, v32
	v_rcp_f32_e32 v33, v33
	v_rcp_f32_e32 v34, v34
	v_rcp_f32_e32 v35, v35
	s_waitcnt vmcnt(14)
; __device__ __forceinline__ unsigned cvt_pk_bf16(float lo, float hi) { unsigned r; asm volatile("v_cvt_pk_bf16_f32 %0, %1, %2" : "=v"(r) : "v"(lo), "v"(hi)); return r; }
; __device__ __forceinline__ float bf_lo(unsigned w) { return __uint_as_float(w << 16); }
; __device__ __forceinline__ float bf_hi(unsigned w) { return __uint_as_float(w & 0xffff0000u); }
; __device__ __forceinline__ float fast_sigmoid(float x) { return __builtin_amdgcn_rcpf(1.0f + __builtin_amdgcn_exp2f(-1.4426950408889634f * x)); }
;     __device__ __forceinline__ void operator()(const f32x4 (&acc)[2][2][4][2], const Unit& u, int wr, int wc, int fr, int fq) const {
;     ...
;             for (int m = 0; m < 4; ++m) { const int row = row0 + ai * HALF + m * 16; const size_t off = (size_t)row * EI + col0;
;                 const size_t offy = ((size_t)((row >> 13) * NG + (col0 >> 4)) * SEQ + (row & (SEQ - 1))) * 16 + (col0 & 15);
; #pragma unroll
;                 for (int bj = 0; bj < 2; ++bj) { const u32x4 yv = *(const u32x4*)(YA + offy + (size_t)bj * 8 * SEQ * 16), zv = *(const u32x4*)(SZ + off + bj * HALF);
;                     const i32x4 q0 = __builtin_bit_cast(i32x4, acc[ai][bj][m][0]), q1 = __builtin_bit_cast(i32x4, acc[ai][bj][m][1]);
;                     const f32x4 g0 = (f32x4){(float)q0[0], (float)q0[1], (float)q0[2], (float)q0[3]} * GATE_DEQ + bv[bj][0], g1 = (f32x4){(float)q1[0], (float)q1[1], (float)q1[2], (float)q1[3]} * GATE_DEQ + bv[bj][1];
;                     float o[8];
;                     o[0] = bf_lo(yv.x) * bf_lo(zv.x) * fast_sigmoid(g0[0]); o[1] = bf_hi(yv.x) * bf_hi(zv.x) * fast_sigmoid(g0[1]);
;                     o[2] = bf_lo(yv.y) * bf_lo(zv.y) * fast_sigmoid(g0[2]); o[3] = bf_hi(yv.y) * bf_hi(zv.y) * fast_sigmoid(g0[3]);
;                     o[4] = bf_lo(yv.z) * bf_lo(zv.z) * fast_sigmoid(g1[0]); o[5] = bf_hi(yv.z) * bf_hi(zv.z) * fast_sigmoid(g1[1]);
;                     o[6] = bf_lo(yv.w) * bf_lo(zv.w) * fast_sigmoid(g1[2]); o[7] = bf_hi(yv.w) * bf_hi(zv.w) * fast_sigmoid(g1[3]);
;                     u32x4 w; w.x = cvt_pk_bf16(o[0], o[1]); w.y = cvt_pk_bf16(o[2], o[3]); w.z = cvt_pk_bf16(o[4], o[5]); w.w = cvt_pk_bf16(o[6], o[7]);
;                     *(u32x4*)(V + off + bj * HALF) = w; } }
	v_lshlrev_b32_e32 v168, 16, v248
	v_and_b32_e32 v169, 0xffff0000, v248
	v_lshlrev_b32_e32 v188, 16, v176
	v_and_b32_e32 v189, 0xffff0000, v176
	v_pk_mul_f32 v[168:169], v[168:169], v[188:189]
	v_pk_mul_f32 v[36:37], v[168:169], v[36:37]
	v_lshlrev_b32_e32 v170, 16, v249
	v_and_b32_e32 v171, 0xffff0000, v249
	v_lshlrev_b32_e32 v190, 16, v177
	v_and_b32_e32 v191, 0xffff0000, v177
	v_pk_mul_f32 v[170:171], v[170:171], v[190:191]
	v_pk_mul_f32 v[38:39], v[170:171], v[38:39]
	v_lshlrev_b32_e32 v168, 16, v250
	v_and_b32_e32 v169, 0xffff0000, v250
	v_lshlrev_b32_e32 v188, 16, v178
	v_and_b32_e32 v189, 0xffff0000, v178
	v_pk_mul_f32 v[168:169], v[168:169], v[188:189]
	v_pk_mul_f32 v[32:33], v[168:169], v[32:33]
	v_lshlrev_b32_e32 v170, 16, v251
	v_and_b32_e32 v171, 0xffff0000, v251
	v_lshlrev_b32_e32 v190, 16, v179
	v_and_b32_e32 v191, 0xffff0000, v179
	v_pk_mul_f32 v[170:171], v[170:171], v[190:191]
	v_pk_mul_f32 v[34:35], v[170:171], v[34:35]
	v_cvt_pk_bf16_f32 v36, v36, v37
	v_cvt_pk_bf16_f32 v37, v38, v39
	v_cvt_pk_bf16_f32 v38, v32, v33
	v_cvt_pk_bf16_f32 v39, v34, v35
	global_store_dwordx4 v239, v[36:39], s[100:101] offset:256
	v_cvt_f32_i32_e32 v28, v28
	v_cvt_f32_i32_e32 v29, v29
	v_cvt_f32_i32_e32 v30, v30
	v_cvt_f32_i32_e32 v31, v31
	v_cvt_f32_i32_e32 v24, v24
	v_cvt_f32_i32_e32 v25, v25
	v_cvt_f32_i32_e32 v26, v26
	v_cvt_f32_i32_e32 v27, v27
	v_pk_fma_f32 v[28:29], v[186:187], v[28:29], v[68:69] op_sel_hi:[0,1,1]
	v_pk_fma_f32 v[30:31], v[186:187], v[30:31], v[70:71] op_sel_hi:[0,1,1]
	v_pk_fma_f32 v[24:25], v[186:187], v[24:25], v[64:65] op_sel_hi:[0,1,1]
	v_pk_fma_f32 v[26:27], v[186:187], v[26:27], v[66:67] op_sel_hi:[0,1,1]
	v_pk_mul_f32 v[28:29], v[28:29], s[32:33] op_sel_hi:[1,0]
	v_pk_mul_f32 v[30:31], v[30:31], s[32:33] op_sel_hi:[1,0]
	v_pk_mul_f32 v[24:25], v[24:25], s[32:33] op_sel_hi:[1,0]
	v_pk_mul_f32 v[26:27], v[26:27], s[32:33] op_sel_hi:[1,0]
	v_exp_f32_e32 v28, v28
	v_exp_f32_e32 v29, v29
	v_exp_f32_e32 v30, v30
	v_exp_f32_e32 v31, v31
	v_exp_f32_e32 v24, v24
	v_exp_f32_e32 v25, v25
	v_exp_f32_e32 v26, v26
	v_exp_f32_e32 v27, v27
	v_pk_add_f32 v[28:29], v[28:29], 1.0 op_sel_hi:[1,0]
	v_pk_add_f32 v[30:31], v[30:31], 1.0 op_sel_hi:[1,0]
	v_pk_add_f32 v[24:25], v[24:25], 1.0 op_sel_hi:[1,0]
	v_pk_add_f32 v[26:27], v[26:27], 1.0 op_sel_hi:[1,0]
	v_rcp_f32_e32 v28, v28
	v_rcp_f32_e32 v29, v29
	v_rcp_f32_e32 v30, v30
	v_rcp_f32_e32 v31, v31
	v_rcp_f32_e32 v24, v24
	v_rcp_f32_e32 v25, v25
	v_rcp_f32_e32 v26, v26
	v_rcp_f32_e32 v27, v27
	s_waitcnt vmcnt(12)
	v_lshlrev_b32_e32 v168, 16, v144
	v_and_b32_e32 v169, 0xffff0000, v144
	v_lshlrev_b32_e32 v188, 16, v148
	v_and_b32_e32 v189, 0xffff0000, v148
	v_pk_mul_f32 v[168:169], v[168:169], v[188:189]
	v_pk_mul_f32 v[28:29], v[168:169], v[28:29]
	v_lshlrev_b32_e32 v170, 16, v145
	v_and_b32_e32 v171, 0xffff0000, v145
	v_lshlrev_b32_e32 v190, 16, v149
	v_and_b32_e32 v191, 0xffff0000, v149
	v_pk_mul_f32 v[170:171], v[170:171], v[190:191]
	v_pk_mul_f32 v[30:31], v[170:171], v[30:31]
	v_lshlrev_b32_e32 v168, 16, v146
	v_and_b32_e32 v169, 0xffff0000, v146
	v_lshlrev_b32_e32 v188, 16, v150
	v_and_b32_e32 v189, 0xffff0000, v150
	v_pk_mul_f32 v[168:169], v[168:169], v[188:189]
	v_pk_mul_f32 v[24:25], v[168:169], v[24:25]
	v_lshlrev_b32_e32 v170, 16, v147
	v_and_b32_e32 v171, 0xffff0000, v147
	v_lshlrev_b32_e32 v190, 16, v151
	v_and_b32_e32 v191, 0xffff0000, v151
	v_pk_mul_f32 v[170:171], v[170:171], v[190:191]
	v_pk_mul_f32 v[26:27], v[170:171], v[26:27]
	v_cvt_pk_bf16_f32 v28, v28, v29
	v_cvt_pk_bf16_f32 v29, v30, v31
	v_cvt_pk_bf16_f32 v30, v24, v25
	v_cvt_pk_bf16_f32 v31, v26, v27
	s_add_u32 s100, s16, 0x280000
	s_addc_u32 s101, s17, 0
	global_store_dwordx4 v239, v[28:31], s[100:101]
	v_cvt_f32_i32_e32 v20, v20
	v_cvt_f32_i32_e32 v21, v21
	v_cvt_f32_i32_e32 v22, v22
	v_cvt_f32_i32_e32 v23, v23
	v_cvt_f32_i32_e32 v16, v16
	v_cvt_f32_i32_e32 v17, v17
	v_cvt_f32_i32_e32 v18, v18
	v_cvt_f32_i32_e32 v19, v19
	v_pk_fma_f32 v[20:21], v[186:187], v[20:21], v[136:137] op_sel_hi:[0,1,1]
	v_pk_fma_f32 v[22:23], v[186:187], v[22:23], v[138:139] op_sel_hi:[0,1,1]
	v_pk_fma_f32 v[16:17], v[186:187], v[16:17], v[140:141] op_sel_hi:[0,1,1]
	v_pk_fma_f32 v[18:19], v[186:187], v[18:19], v[142:143] op_sel_hi:[0,1,1]
	v_pk_mul_f32 v[20:21], v[20:21], s[32:33] op_sel_hi:[1,0]
	v_pk_mul_f32 v[22:23], v[22:23], s[32:33] op_sel_hi:[1,0]
	v_pk_mul_f32 v[16:17], v[16:17], s[32:33] op_sel_hi:[1,0]
	v_pk_mul_f32 v[18:19], v[18:19], s[32:33] op_sel_hi:[1,0]
	v_exp_f32_e32 v20, v20
	v_exp_f32_e32 v21, v21
	v_exp_f32_e32 v22, v22
	v_exp_f32_e32 v23, v23
	v_exp_f32_e32 v16, v16
	v_exp_f32_e32 v17, v17
	v_exp_f32_e32 v18, v18
	v_exp_f32_e32 v19, v19
	v_pk_add_f32 v[20:21], v[20:21], 1.0 op_sel_hi:[1,0]
	v_pk_add_f32 v[22:23], v[22:23], 1.0 op_sel_hi:[1,0]
	v_pk_add_f32 v[16:17], v[16:17], 1.0 op_sel_hi:[1,0]
	v_pk_add_f32 v[18:19], v[18:19], 1.0 op_sel_hi:[1,0]
	v_rcp_f32_e32 v20, v20
	v_rcp_f32_e32 v21, v21
	v_rcp_f32_e32 v22, v22
	v_rcp_f32_e32 v23, v23
	v_rcp_f32_e32 v16, v16
	v_rcp_f32_e32 v17, v17
	v_rcp_f32_e32 v18, v18
	v_rcp_f32_e32 v19, v19
	s_waitcnt vmcnt(10)
; __device__ __forceinline__ unsigned cvt_pk_bf16(float lo, float hi) { unsigned r; asm volatile("v_cvt_pk_bf16_f32 %0, %1, %2" : "=v"(r) : "v"(lo), "v"(hi)); return r; }
; __device__ __forceinline__ float bf_lo(unsigned w) { return __uint_as_float(w << 16); }
; __device__ __forceinline__ float bf_hi(unsigned w) { return __uint_as_float(w & 0xffff0000u); }
; __device__ __forceinline__ float fast_sigmoid(float x) { return __builtin_amdgcn_rcpf(1.0f + __builtin_amdgcn_exp2f(-1.4426950408889634f * x)); }
;     __device__ __forceinline__ void operator()(const f32x4 (&acc)[2][2][4][2], const Unit& u, int wr, int wc, int fr, int fq) const {
;     ...
;             for (int m = 0; m < 4; ++m) { const int row = row0 + ai * HALF + m * 16; const size_t off = (size_t)row * EI + col0;
;                 const size_t offy = ((size_t)((row >> 13) * NG + (col0 >> 4)) * SEQ + (row & (SEQ - 1))) * 16 + (col0 & 15);
; #pragma unroll
;                 for (int bj = 0; bj < 2; ++bj) { const u32x4 yv = *(const u32x4*)(YA + offy + (size_t)bj * 8 * SEQ * 16), zv = *(const u32x4*)(SZ + off + bj * HALF);
;                     const i32x4 q0 = __builtin_bit_cast(i32x4, acc[ai][bj][m][0]), q1 = __builtin_bit_cast(i32x4, acc[ai][bj][m][1]);
;                     const f32x4 g0 = (f32x4){(float)q0[0], (float)q0[1], (float)q0[2], (float)q0[3]} * GATE_DEQ + bv[bj][0], g1 = (f32x4){(float)q1[0], (float)q1[1], (float)q1[2], (float)q1[3]} * GATE_DEQ + bv[bj][1];
;                     float o[8];
;                     o[0] = bf_lo(yv.x) * bf_lo(zv.x) * fast_sigmoid(g0[0]); o[1] = bf_hi(yv.x) * bf_hi(zv.x) * fast_sigmoid(g0[1]);
;                     o[2] = bf_lo(yv.y) * bf_lo(zv.y) * fast_sigmoid(g0[2]); o[3] = bf_hi(yv.y) * bf_hi(zv.y) * fast_sigmoid(g0[3]);
;                     o[4] = bf_lo(yv.z) * bf_lo(zv.z) * fast_sigmoid(g1[0]); o[5] = bf_hi(yv.z) * bf_hi(zv.z) * fast_sigmoid(g1[1]);
;                     o[6] = bf_lo(yv.w) * bf_lo(zv.w) * fast_sigmoid(g1[2]); o[7] = bf_hi(yv.w) * bf_hi(zv.w) * fast_sigmoid(g1[3]);
;                     u32x4 w; w.x = cvt_pk_bf16(o[0], o[1]); w.y = cvt_pk_bf16(o[2], o[3]); w.z = cvt_pk_bf16(o[4], o[5]); w.w = cvt_pk_bf16(o[6], o[7]);
;                     *(u32x4*)(V + off + bj * HALF) = w; } }
	v_lshlrev_b32_e32 v168, 16, v152
	v_and_b32_e32 v169, 0xffff0000, v152
	v_lshlrev_b32_e32 v188, 16, v156
	v_and_b32_e32 v189, 0xffff0000, v156
	v_pk_mul_f32 v[168:169], v[168:169], v[188:189]
	v_pk_mul_f32 v[20:21], v[168:169], v[20:21]
	v_lshlrev_b32_e32 v170, 16, v153
	v_and_b32_e32 v171, 0xffff0000, v153
	v_lshlrev_b32_e32 v190, 16, v157
	v_and_b32_e32 v191, 0xffff0000, v157
	v_pk_mul_f32 v[170:171], v[170:171], v[190:191]
	v_pk_mul_f32 v[22:23], v[170:171], v[22:23]
	v_lshlrev_b32_e32 v168, 16, v154
	v_and_b32_e32 v169, 0xffff0000, v154
	v_lshlrev_b32_e32 v188, 16, v158
	v_and_b32_e32 v189, 0xffff0000, v158
	v_pk_mul_f32 v[168:169], v[168:169], v[188:189]
	v_pk_mul_f32 v[16:17], v[168:169], v[16:17]
	v_lshlrev_b32_e32 v170, 16, v155
	v_and_b32_e32 v171, 0xffff0000, v155
	v_lshlrev_b32_e32 v190, 16, v159
	v_and_b32_e32 v191, 0xffff0000, v159
	v_pk_mul_f32 v[170:171], v[170:171], v[190:191]
	v_pk_mul_f32 v[18:19], v[170:171], v[18:19]
	v_cvt_pk_bf16_f32 v20, v20, v21
	v_cvt_pk_bf16_f32 v21, v22, v23
	v_cvt_pk_bf16_f32 v22, v16, v17
	v_cvt_pk_bf16_f32 v23, v18, v19
	global_store_dwordx4 v239, v[20:23], s[100:101] offset:256
	v_cvt_f32_i32_e32 v12, v12
	v_cvt_f32_i32_e32 v13, v13
	v_cvt_f32_i32_e32 v14, v14
	v_cvt_f32_i32_e32 v15, v15
	v_cvt_f32_i32_e32 v8, v8
	v_cvt_f32_i32_e32 v9, v9
	v_cvt_f32_i32_e32 v10, v10
	v_cvt_f32_i32_e32 v11, v11
	v_pk_fma_f32 v[12:13], v[186:187], v[12:13], v[68:69] op_sel_hi:[0,1,1]
	v_pk_fma_f32 v[14:15], v[186:187], v[14:15], v[70:71] op_sel_hi:[0,1,1]
	v_pk_fma_f32 v[8:9], v[186:187], v[8:9], v[64:65] op_sel_hi:[0,1,1]
	v_pk_fma_f32 v[10:11], v[186:187], v[10:11], v[66:67] op_sel_hi:[0,1,1]
	v_pk_mul_f32 v[12:13], v[12:13], s[32:33] op_sel_hi:[1,0]
	v_pk_mul_f32 v[14:15], v[14:15], s[32:33] op_sel_hi:[1,0]
	v_pk_mul_f32 v[8:9], v[8:9], s[32:33] op_sel_hi:[1,0]
	v_pk_mul_f32 v[10:11], v[10:11], s[32:33] op_sel_hi:[1,0]
	v_exp_f32_e32 v12, v12
	v_exp_f32_e32 v13, v13
	v_exp_f32_e32 v14, v14
	v_exp_f32_e32 v15, v15
	v_exp_f32_e32 v8, v8
	v_exp_f32_e32 v9, v9
	v_exp_f32_e32 v10, v10
	v_exp_f32_e32 v11, v11
	v_pk_add_f32 v[12:13], v[12:13], 1.0 op_sel_hi:[1,0]
	v_pk_add_f32 v[14:15], v[14:15], 1.0 op_sel_hi:[1,0]
	v_pk_add_f32 v[8:9], v[8:9], 1.0 op_sel_hi:[1,0]
	v_pk_add_f32 v[10:11], v[10:11], 1.0 op_sel_hi:[1,0]
	v_rcp_f32_e32 v12, v12
	v_rcp_f32_e32 v13, v13
	v_rcp_f32_e32 v14, v14
	v_rcp_f32_e32 v15, v15
	v_rcp_f32_e32 v8, v8
	v_rcp_f32_e32 v9, v9
	v_rcp_f32_e32 v10, v10
	v_rcp_f32_e32 v11, v11
	s_waitcnt vmcnt(8)
	v_lshlrev_b32_e32 v168, 16, v160
	v_and_b32_e32 v169, 0xffff0000, v160
	v_lshlrev_b32_e32 v188, 16, v164
	v_and_b32_e32 v189, 0xffff0000, v164
	v_pk_mul_f32 v[168:169], v[168:169], v[188:189]
	v_pk_mul_f32 v[12:13], v[168:169], v[12:13]
	v_lshlrev_b32_e32 v170, 16, v161
	v_and_b32_e32 v171, 0xffff0000, v161
	v_lshlrev_b32_e32 v190, 16, v165
	v_and_b32_e32 v191, 0xffff0000, v165
	v_pk_mul_f32 v[170:171], v[170:171], v[190:191]
	v_pk_mul_f32 v[14:15], v[170:171], v[14:15]
	v_lshlrev_b32_e32 v168, 16, v162
	v_and_b32_e32 v169, 0xffff0000, v162
	v_lshlrev_b32_e32 v188, 16, v166
	v_and_b32_e32 v189, 0xffff0000, v166
	v_pk_mul_f32 v[168:169], v[168:169], v[188:189]
	v_pk_mul_f32 v[8:9], v[168:169], v[8:9]
	v_lshlrev_b32_e32 v170, 16, v163
	v_and_b32_e32 v171, 0xffff0000, v163
	v_lshlrev_b32_e32 v190, 16, v167
	v_and_b32_e32 v191, 0xffff0000, v167
	v_pk_mul_f32 v[170:171], v[170:171], v[190:191]
	v_pk_mul_f32 v[10:11], v[170:171], v[10:11]
	v_cvt_pk_bf16_f32 v12, v12, v13
	v_cvt_pk_bf16_f32 v13, v14, v15
	v_cvt_pk_bf16_f32 v14, v8, v9
	v_cvt_pk_bf16_f32 v15, v10, v11
	s_add_u32 s100, s16, 0x2c0000
	s_addc_u32 s101, s17, 0
	global_store_dwordx4 v239, v[12:15], s[100:101]
	v_cvt_f32_i32_e32 v4, v4
	v_cvt_f32_i32_e32 v5, v5
	v_cvt_f32_i32_e32 v6, v6
	v_cvt_f32_i32_e32 v7, v7
	v_cvt_f32_i32_e32 v0, v0
	v_cvt_f32_i32_e32 v1, v1
	v_cvt_f32_i32_e32 v2, v2
	v_cvt_f32_i32_e32 v3, v3
	v_pk_fma_f32 v[4:5], v[186:187], v[4:5], v[136:137] op_sel_hi:[0,1,1]
	v_pk_fma_f32 v[6:7], v[186:187], v[6:7], v[138:139] op_sel_hi:[0,1,1]
	v_pk_fma_f32 v[0:1], v[186:187], v[0:1], v[140:141] op_sel_hi:[0,1,1]
	v_pk_fma_f32 v[2:3], v[186:187], v[2:3], v[142:143] op_sel_hi:[0,1,1]
	v_pk_mul_f32 v[4:5], v[4:5], s[32:33] op_sel_hi:[1,0]
	v_pk_mul_f32 v[6:7], v[6:7], s[32:33] op_sel_hi:[1,0]
	v_pk_mul_f32 v[0:1], v[0:1], s[32:33] op_sel_hi:[1,0]
	v_pk_mul_f32 v[2:3], v[2:3], s[32:33] op_sel_hi:[1,0]
	v_exp_f32_e32 v4, v4
	v_exp_f32_e32 v5, v5
	v_exp_f32_e32 v6, v6
	v_exp_f32_e32 v7, v7
	v_exp_f32_e32 v0, v0
	v_exp_f32_e32 v1, v1
	v_exp_f32_e32 v2, v2
	v_exp_f32_e32 v3, v3
	v_pk_add_f32 v[4:5], v[4:5], 1.0 op_sel_hi:[1,0]
	v_pk_add_f32 v[6:7], v[6:7], 1.0 op_sel_hi:[1,0]
	v_pk_add_f32 v[0:1], v[0:1], 1.0 op_sel_hi:[1,0]
	v_pk_add_f32 v[2:3], v[2:3], 1.0 op_sel_hi:[1,0]
	v_rcp_f32_e32 v4, v4
	v_rcp_f32_e32 v5, v5
	v_rcp_f32_e32 v6, v6
	v_rcp_f32_e32 v7, v7
	v_rcp_f32_e32 v0, v0
	v_rcp_f32_e32 v1, v1
	v_rcp_f32_e32 v2, v2
	v_rcp_f32_e32 v3, v3
	s_waitcnt vmcnt(6)
	v_lshlrev_b32_e32 v168, 16, v172
	v_and_b32_e32 v169, 0xffff0000, v172
	v_lshlrev_b32_e32 v188, 16, v180
	v_and_b32_e32 v189, 0xffff0000, v180
	v_pk_mul_f32 v[168:169], v[168:169], v[188:189]
	v_pk_mul_f32 v[4:5], v[168:169], v[4:5]
	v_lshlrev_b32_e32 v170, 16, v173
	v_and_b32_e32 v171, 0xffff0000, v173
	v_lshlrev_b32_e32 v190, 16, v181
	v_and_b32_e32 v191, 0xffff0000, v181
	v_pk_mul_f32 v[170:171], v[170:171], v[190:191]
	v_pk_mul_f32 v[6:7], v[170:171], v[6:7]
	v_lshlrev_b32_e32 v168, 16, v174
	v_and_b32_e32 v169, 0xffff0000, v174
	v_lshlrev_b32_e32 v188, 16, v182
	v_and_b32_e32 v189, 0xffff0000, v182
	v_pk_mul_f32 v[168:169], v[168:169], v[188:189]
	v_pk_mul_f32 v[0:1], v[168:169], v[0:1]
	v_lshlrev_b32_e32 v170, 16, v175
	v_and_b32_e32 v171, 0xffff0000, v175
	v_lshlrev_b32_e32 v190, 16, v183
	v_and_b32_e32 v191, 0xffff0000, v183
	v_pk_mul_f32 v[170:171], v[170:171], v[190:191]
	v_pk_mul_f32 v[2:3], v[170:171], v[2:3]
	v_cvt_pk_bf16_f32 v4, v4, v5
	v_cvt_pk_bf16_f32 v5, v6, v7
	v_cvt_pk_bf16_f32 v6, v0, v1
	v_cvt_pk_bf16_f32 v7, v2, v3
	global_store_dwordx4 v239, v[4:7], s[100:101] offset:256
	s_andn2_b64 vcc, exec, s[42:43]
	s_mov_b64 s[42:43], -1
	s_cbranch_vccnz .LBB0_483
	s_andn2_b64 vcc, exec, s[4:5]
	s_cbranch_vccnz .LBB0_482
	s_barrier
	s_branch .LBB0_482

; #define LAS __attribute__((address_space(3)))
; __global__ void __launch_bounds__(NWAVES * 64, 2) trunk_fwd(Args a) {
;     extern __shared__ __attribute__((aligned(16))) unsigned char lds_raw[];
;     Ctx F; F.lds = (LAS unsigned char*)lds_raw; F.tid = threadIdx.x; F.lane = F.tid & 63; F.wave = __builtin_amdgcn_readfirstlane(F.tid >> 6);
;     F.G = gridDim.x; F.wg = blockIdx.x;
	.amdhsa_kernel _Z9trunk_fwd4Args
		.amdhsa_group_segment_fixed_size 0
		.amdhsa_private_segment_fixed_size 0
		.amdhsa_kernarg_size 456
		.amdhsa_user_sgpr_count 2
		.amdhsa_user_sgpr_dispatch_ptr 0
		.amdhsa_user_sgpr_queue_ptr 0
		.amdhsa_user_sgpr_kernarg_segment_ptr 1
		.amdhsa_user_sgpr_dispatch_id 0
		.amdhsa_user_sgpr_kernarg_preload_length 0
		.amdhsa_user_sgpr_kernarg_preload_offset 0
		.amdhsa_user_sgpr_private_segment_size 0
		.amdhsa_uses_dynamic_stack 0
		.amdhsa_enable_private_segment 0
		.amdhsa_system_sgpr_workgroup_id_x 1
		.amdhsa_system_sgpr_workgroup_id_y 0
		.amdhsa_system_sgpr_workgroup_id_z 0
		.amdhsa_system_sgpr_workgroup_info 0
		.amdhsa_system_vgpr_workitem_id 0
		.amdhsa_next_free_vgpr 256
		.amdhsa_next_free_sgpr 102
		.amdhsa_accum_offset 256
		.amdhsa_reserve_vcc 1
		.amdhsa_float_round_mode_32 0
		.amdhsa_float_round_mode_16_64 0
		.amdhsa_float_denorm_mode_32 3
		.amdhsa_float_denorm_mode_16_64 3
		.amdhsa_dx10_clamp 1
		.amdhsa_ieee_mode 1
		.amdhsa_fp16_overflow 0
		.amdhsa_tg_split 0
		.amdhsa_exception_fp_ieee_invalid_op 0
		.amdhsa_exception_fp_denorm_src 0
		.amdhsa_exception_fp_ieee_div_zero 0
		.amdhsa_exception_fp_ieee_overflow 0
		.amdhsa_exception_fp_ieee_underflow 0
		.amdhsa_exception_fp_ieee_inexact 0
		.amdhsa_exception_int_div_zero 0
	.end_amdhsa_kernel

; #define LAS __attribute__((address_space(3)))
; __global__ void __launch_bounds__(NWAVES * 64, 2) trunk_fwd(Args a) {
;     extern __shared__ __attribute__((aligned(16))) unsigned char lds_raw[];
;     Ctx F; F.lds = (LAS unsigned char*)lds_raw; F.tid = threadIdx.x; F.lane = F.tid & 63; F.wave = __builtin_amdgcn_readfirstlane(F.tid >> 6);
;     F.G = gridDim.x; F.wg = blockIdx.x;
amdhsa.kernels:
  - .agpr_count:     0
    .args:
      - .offset:         0
        .size:           200
        .value_kind:     by_value
      - .offset:         200
        .size:           4
        .value_kind:     hidden_block_count_x
      - .offset:         204
        .size:           4
        .value_kind:     hidden_block_count_y
      - .offset:         208
        .size:           4
        .value_kind:     hidden_block_count_z
      - .offset:         212
        .size:           2
        .value_kind:     hidden_group_size_x
      - .offset:         214
        .size:           2
        .value_kind:     hidden_group_size_y
      - .offset:         216
        .size:           2
        .value_kind:     hidden_group_size_z
      - .offset:         218
        .size:           2
        .value_kind:     hidden_remainder_x
      - .offset:         220
        .size:           2
        .value_kind:     hidden_remainder_y
      - .offset:         222
        .size:           2
        .value_kind:     hidden_remainder_z
      - .offset:         240
        .size:           8
        .value_kind:     hidden_global_offset_x
      - .offset:         248
        .size:           8
        .value_kind:     hidden_global_offset_y
      - .offset:         256
        .size:           8
        .value_kind:     hidden_global_offset_z
      - .offset:         264
        .size:           2
        .value_kind:     hidden_grid_dims
      - .offset:         320
        .size:           4
        .value_kind:     hidden_dynamic_lds_size
    .group_segment_fixed_size: 0
    .kernarg_segment_align: 8
    .kernarg_segment_size: 456
    .language:       OpenCL C
    .language_version:
      - 2
      - 0
    .max_flat_workgroup_size: 512
    .name:           _Z9trunk_fwd4Args
    .private_segment_fixed_size: 0
    .sgpr_count:     108
    .sgpr_spill_count: 18
    .symbol:         _Z9trunk_fwd4Args.kd
    .uniform_work_group_size: 1
    .uses_dynamic_stack: false
    .vgpr_count:     256
    .vgpr_spill_count: 0
    .wavefront_size: 64
